# v23 + retc groupnorm reductions: 16 ds_bpermute butterfly hops replaced by DPP row adds (bit-identical sums)
# speedup vs baseline: 1.0017x; 1.0017x over previous
; #define LAS __attribute__((address_space(3)))
; #define MFMA16(a, b, c) __builtin_amdgcn_mfma_f32_16x16x32_bf16((a), (b), (c), 0, 0, 0)
; #define WAITV0() asm volatile("s_waitcnt vmcnt(0)" ::: "memory")
; #define LBAR() do { asm volatile("s_waitcnt lgkmcnt(0)" ::: "memory"); __builtin_amdgcn_s_barrier(); asm volatile("" ::: "memory"); } while (0)
; __device__ __forceinline__ void retc_stream(const int wv, LAS unsigned char* lds, unsigned ldsb, const float* __restrict__ gn_g, const float* __restrict__ gn_b, const bf16_t* __restrict__ qkvr, const bf16_t* __restrict__ grb, const bf16_t* __restrict__ kv, ...
;     ...
;         const float lg2 = log2f(1.0f - exp2f(-5.0f - (float)h));
;     ...
; #pragma unroll
;         for (int vc = 0; vc < 4; ++vc) {
;             WAITV0(); LBAR();
;             if (vc < 3) RETC_ISSUE(item, 5 + vc);
;             unsigned img = (vc & 1) * 65536u; asm volatile("" : "+v"(img));
; #pragma unroll
;             for (int s = 0; s < 8; ++s) {
;                 bf16x8 bfr[8];
; #pragma unroll
;                 for (int c = 0; c < 8; ++c) bfr[c] = *(const LAS bf16x8*)(lds + img + c * 8192 + koff[s]);
;                 asm volatile("s_waitcnt lgkmcnt(0)" ::: "memory");
; #pragma unroll
;                 for (int c = 0; c < 8; ++c) acc[vc * 8 + c] = MFMA16(qf[s], bfr[c], acc[vc * 8 + c]);
;             }
;         }
.LBB0_500:
	v_cvt_f32_i32_e32 v1, s40
	s_mov_b32 s41, 0xc2fc0000
	s_waitcnt vmcnt(0)
	s_waitcnt lgkmcnt(0)
	v_sub_f32_e32 v1, 0xc0a00000, v1
	v_cmp_gt_f32_e32 vcc, s41, v1
	s_and_b64 s[0:1], vcc, exec
	s_cselect_b32 s0, 0xffffffc0, 0
	v_cndmask_b32_e32 v2, 0, v187, vcc
	v_add_f32_e32 v1, v1, v2
	v_exp_f32_e32 v1, v1
	s_barrier
	s_mov_b32 m0, s46
	v_ldexp_f32 v1, v1, s0
	v_sub_f32_e32 v1, 1.0, v1
	v_cmp_gt_f32_e32 vcc, s36, v1
	s_and_b64 s[0:1], vcc, exec
	s_cselect_b32 s0, 32, 0
	v_ldexp_f32 v1, v1, s0
	v_log_f32_e32 v1, v1
	v_readlane_b32 s0, v254, 2
	v_readlane_b32 s1, v254, 3
	v_cndmask_b32_e32 v2, 0, v190, vcc
	s_add_i32 s28, s28, s0
	s_mov_b64 s[0:1], 0x10000
	v_sub_f32_e32 v1, v1, v2
	v_lshl_add_u64 v[2:3], v[182:183], 0, s[0:1]
	s_mov_b64 s[0:1], 0x12000
	global_load_lds_dwordx4 v[2:3], off nt
	v_lshl_add_u64 v[2:3], v[182:183], 0, s[0:1]
	s_mov_b32 m0, s53
	s_mov_b64 s[0:1], 0x14000
	global_load_lds_dwordx4 v[2:3], off nt
	v_lshl_add_u64 v[2:3], v[182:183], 0, s[0:1]
	s_mov_b32 m0, s52
	s_mov_b64 s[0:1], 0x16000
	global_load_lds_dwordx4 v[2:3], off nt
	v_lshl_add_u64 v[2:3], v[182:183], 0, s[0:1]
	s_mov_b32 m0, s55
	s_mov_b64 s[0:1], 0x18000
	global_load_lds_dwordx4 v[2:3], off nt
	v_lshl_add_u64 v[2:3], v[182:183], 0, s[0:1]
	s_mov_b32 m0, s54
	s_mov_b64 s[0:1], 0x1a000
	global_load_lds_dwordx4 v[2:3], off nt
	v_lshl_add_u64 v[2:3], v[182:183], 0, s[0:1]
	s_mov_b32 m0, s57
	s_mov_b64 s[0:1], 0x1c000
	global_load_lds_dwordx4 v[2:3], off nt
	v_lshl_add_u64 v[2:3], v[182:183], 0, s[0:1]
	s_mov_b32 m0, s56
	s_mov_b64 s[0:1], 0x1e000
	global_load_lds_dwordx4 v[2:3], off nt
	v_lshl_add_u64 v[2:3], v[182:183], 0, s[0:1]
	s_mov_b32 m0, s59
	s_mov_b64 s[0:1], 0x20000
	global_load_lds_dwordx4 v[2:3], off nt
	v_mov_b32_e32 v2, v0
	s_mov_b32 m0, s58
	v_add_u32_e32 v242, 0, v2
	v_add_u32_e32 v2, v242, v192
	ds_read_b128 v[166:169], v2
	ds_read_b128 v[170:173], v2 offset:8192
	ds_read_b128 v[174:177], v2 offset:16384
	ds_read_b128 v[222:225], v2 offset:24576
	ds_read_b128 v[226:229], v2 offset:32768
	ds_read_b128 v[230:233], v2 offset:40960
	ds_read_b128 v[234:237], v2 offset:49152
	ds_read_b128 v[238:241], v2 offset:57344
	s_waitcnt lgkmcnt(0)
	s_waitcnt lgkmcnt(0)
	v_mfma_f32_16x16x32_bf16 v[2:5], v[62:65], v[222:225], v[4:7]
	s_lshl_b32 s2, s40, 9
	s_mov_b32 s40, 0x3b000000
	s_ashr_i32 s3, s2, 31
	v_add_u32_e32 v6, v242, v193
	v_mfma_f32_16x16x32_bf16 v[16:19], v[62:65], v[166:169], v[16:19]
	s_lshl_b64 s[12:13], s[2:3], 2
	s_add_u32 s10, s16, s12
	s_addc_u32 s11, s17, s13
	v_mfma_f32_16x16x32_bf16 v[12:15], v[62:65], v[170:173], v[12:15]
	s_lshl_b32 s29, s29, 7
	v_mfma_f32_16x16x32_bf16 v[8:11], v[62:65], v[174:177], v[8:11]
	v_mfma_f32_16x16x32_bf16 v[162:165], v[62:65], v[226:229], v[162:165]
	v_mfma_f32_16x16x32_bf16 v[28:31], v[62:65], v[230:233], v[28:31]
	v_mfma_f32_16x16x32_bf16 v[24:27], v[62:65], v[234:237], v[24:27]
	v_mfma_f32_16x16x32_bf16 v[20:23], v[62:65], v[238:241], v[20:23]
	ds_read_b128 v[166:169], v6
	ds_read_b128 v[170:173], v6 offset:8192
	ds_read_b128 v[174:177], v6 offset:16384
	ds_read_b128 v[222:225], v6 offset:24576
	ds_read_b128 v[226:229], v6 offset:32768
	ds_read_b128 v[230:233], v6 offset:40960
	ds_read_b128 v[234:237], v6 offset:49152
	ds_read_b128 v[238:241], v6 offset:57344
	s_waitcnt lgkmcnt(0)
	s_waitcnt lgkmcnt(0)
	v_mfma_f32_16x16x32_bf16 v[6:9], v[58:61], v[174:177], v[8:11]
	s_nop 2
	v_add_u32_e32 v10, v242, v194
	v_mfma_f32_16x16x32_bf16 v[16:19], v[58:61], v[166:169], v[16:19]
	v_mfma_f32_16x16x32_bf16 v[12:15], v[58:61], v[170:173], v[12:15]
	v_mfma_f32_16x16x32_bf16 v[2:5], v[58:61], v[222:225], v[2:5]
	v_mfma_f32_16x16x32_bf16 v[162:165], v[58:61], v[226:229], v[162:165]
	v_mfma_f32_16x16x32_bf16 v[28:31], v[58:61], v[230:233], v[28:31]
	v_mfma_f32_16x16x32_bf16 v[24:27], v[58:61], v[234:237], v[24:27]
	v_mfma_f32_16x16x32_bf16 v[20:23], v[58:61], v[238:241], v[20:23]
	ds_read_b128 v[166:169], v10
	ds_read_b128 v[170:173], v10 offset:8192
	ds_read_b128 v[174:177], v10 offset:16384
	ds_read_b128 v[222:225], v10 offset:24576
	ds_read_b128 v[226:229], v10 offset:32768
	ds_read_b128 v[230:233], v10 offset:40960
	ds_read_b128 v[234:237], v10 offset:49152
	ds_read_b128 v[238:241], v10 offset:57344
	s_waitcnt lgkmcnt(0)
	s_waitcnt lgkmcnt(0)
	v_mfma_f32_16x16x32_bf16 v[10:13], v[54:57], v[170:173], v[12:15]
	s_nop 2
	v_add_u32_e32 v14, v242, v195
	v_mfma_f32_16x16x32_bf16 v[16:19], v[54:57], v[166:169], v[16:19]
	v_mfma_f32_16x16x32_bf16 v[6:9], v[54:57], v[174:177], v[6:9]
	v_mfma_f32_16x16x32_bf16 v[2:5], v[54:57], v[222:225], v[2:5]
	v_mfma_f32_16x16x32_bf16 v[162:165], v[54:57], v[226:229], v[162:165]
	v_mfma_f32_16x16x32_bf16 v[28:31], v[54:57], v[230:233], v[28:31]
	v_mfma_f32_16x16x32_bf16 v[24:27], v[54:57], v[234:237], v[24:27]
	v_mfma_f32_16x16x32_bf16 v[20:23], v[54:57], v[238:241], v[20:23]
	ds_read_b128 v[166:169], v14
	ds_read_b128 v[170:173], v14 offset:8192
	ds_read_b128 v[174:177], v14 offset:16384
	ds_read_b128 v[222:225], v14 offset:24576
	ds_read_b128 v[226:229], v14 offset:32768
	ds_read_b128 v[230:233], v14 offset:40960
	ds_read_b128 v[234:237], v14 offset:49152
	ds_read_b128 v[238:241], v14 offset:57344
	s_waitcnt lgkmcnt(0)
	s_waitcnt lgkmcnt(0)
; #define LAS __attribute__((address_space(3)))
; #define MFMA16(a, b, c) __builtin_amdgcn_mfma_f32_16x16x32_bf16((a), (b), (c), 0, 0, 0)
; #define WAITV0() asm volatile("s_waitcnt vmcnt(0)" ::: "memory")
; #define LBAR() do { asm volatile("s_waitcnt lgkmcnt(0)" ::: "memory"); __builtin_amdgcn_s_barrier(); asm volatile("" ::: "memory"); } while (0)
; __device__ __forceinline__ void retc_stream(const int wv, LAS unsigned char* lds, unsigned ldsb, const float* __restrict__ gn_g, const float* __restrict__ gn_b, const bf16_t* __restrict__ qkvr, const bf16_t* __restrict__ grb, const bf16_t* __restrict__ kv, ...
;     ...
; #pragma unroll
;         for (int vc = 0; vc < 4; ++vc) {
;             WAITV0(); LBAR();
;             if (vc < 3) RETC_ISSUE(item, 5 + vc);
;             unsigned img = (vc & 1) * 65536u; asm volatile("" : "+v"(img));
; #pragma unroll
;             for (int s = 0; s < 8; ++s) {
;                 bf16x8 bfr[8];
; #pragma unroll
;                 for (int c = 0; c < 8; ++c) bfr[c] = *(const LAS bf16x8*)(lds + img + c * 8192 + koff[s]);
;                 asm volatile("s_waitcnt lgkmcnt(0)" ::: "memory");
; #pragma unroll
;                 for (int c = 0; c < 8; ++c) acc[vc * 8 + c] = MFMA16(qf[s], bfr[c], acc[vc * 8 + c]);
;             }
;         }
	v_mfma_f32_16x16x32_bf16 v[14:17], v[50:53], v[166:169], v[16:19]
	v_mfma_f32_16x16x32_bf16 v[18:21], v[50:53], v[238:241], v[20:23]
	s_nop 2
	v_add_u32_e32 v22, v242, v196
	v_mfma_f32_16x16x32_bf16 v[10:13], v[50:53], v[170:173], v[10:13]
	v_mfma_f32_16x16x32_bf16 v[6:9], v[50:53], v[174:177], v[6:9]
	v_mfma_f32_16x16x32_bf16 v[2:5], v[50:53], v[222:225], v[2:5]
	v_mfma_f32_16x16x32_bf16 v[162:165], v[50:53], v[226:229], v[162:165]
	v_mfma_f32_16x16x32_bf16 v[28:31], v[50:53], v[230:233], v[28:31]
	v_mfma_f32_16x16x32_bf16 v[24:27], v[50:53], v[234:237], v[24:27]
	ds_read_b128 v[166:169], v22
	ds_read_b128 v[170:173], v22 offset:8192
	ds_read_b128 v[174:177], v22 offset:16384
	ds_read_b128 v[222:225], v22 offset:24576
	ds_read_b128 v[226:229], v22 offset:32768
	ds_read_b128 v[230:233], v22 offset:40960
	ds_read_b128 v[234:237], v22 offset:49152
	ds_read_b128 v[238:241], v22 offset:57344
	s_waitcnt lgkmcnt(0)
	s_waitcnt lgkmcnt(0)
	v_mfma_f32_16x16x32_bf16 v[22:25], v[46:49], v[234:237], v[24:27]
	s_nop 2
	v_add_u32_e32 v26, v242, v197
	v_mfma_f32_16x16x32_bf16 v[14:17], v[46:49], v[166:169], v[14:17]
	v_mfma_f32_16x16x32_bf16 v[10:13], v[46:49], v[170:173], v[10:13]
	v_mfma_f32_16x16x32_bf16 v[6:9], v[46:49], v[174:177], v[6:9]
	v_mfma_f32_16x16x32_bf16 v[2:5], v[46:49], v[222:225], v[2:5]
	v_mfma_f32_16x16x32_bf16 v[162:165], v[46:49], v[226:229], v[162:165]
	v_mfma_f32_16x16x32_bf16 v[28:31], v[46:49], v[230:233], v[28:31]
	v_mfma_f32_16x16x32_bf16 v[18:21], v[46:49], v[238:241], v[18:21]
	ds_read_b128 v[166:169], v26
	ds_read_b128 v[170:173], v26 offset:8192
	ds_read_b128 v[174:177], v26 offset:16384
	ds_read_b128 v[222:225], v26 offset:24576
	ds_read_b128 v[226:229], v26 offset:32768
	ds_read_b128 v[230:233], v26 offset:40960
	ds_read_b128 v[234:237], v26 offset:49152
	ds_read_b128 v[238:241], v26 offset:57344
	s_waitcnt lgkmcnt(0)
	s_waitcnt lgkmcnt(0)
	v_mfma_f32_16x16x32_bf16 v[14:17], v[42:45], v[166:169], v[14:17]
	v_mfma_f32_16x16x32_bf16 v[162:165], v[42:45], v[226:229], v[162:165]
	v_mfma_f32_16x16x32_bf16 v[22:25], v[42:45], v[234:237], v[22:25]
	v_add_u32_e32 v234, v242, v198
	v_mfma_f32_16x16x32_bf16 v[10:13], v[42:45], v[170:173], v[10:13]
	v_mfma_f32_16x16x32_bf16 v[6:9], v[42:45], v[174:177], v[6:9]
	v_mfma_f32_16x16x32_bf16 v[2:5], v[42:45], v[222:225], v[2:5]
	v_mfma_f32_16x16x32_bf16 v[26:29], v[42:45], v[230:233], v[28:31]
	s_nop 2
	ds_read_b128 v[30:33], v234
	ds_read_b128 v[166:169], v234 offset:8192
	ds_read_b128 v[170:173], v234 offset:16384
	ds_read_b128 v[174:177], v234 offset:24576
	ds_read_b128 v[222:225], v234 offset:32768
	ds_read_b128 v[226:229], v234 offset:40960
	ds_read_b128 v[230:233], v234 offset:49152
	ds_read_b128 v[234:237], v234 offset:57344
	s_waitcnt lgkmcnt(0)
	v_mfma_f32_16x16x32_bf16 v[18:21], v[42:45], v[238:241], v[18:21]
	s_waitcnt lgkmcnt(0)
	v_mfma_f32_16x16x32_bf16 v[14:17], v[38:41], v[30:33], v[14:17]
	v_mfma_f32_16x16x32_bf16 v[162:165], v[38:41], v[222:225], v[162:165]
	v_mfma_f32_16x16x32_bf16 v[10:13], v[38:41], v[166:169], v[10:13]
	v_mfma_f32_16x16x32_bf16 v[166:169], v[38:41], v[226:229], v[26:29]
	s_nop 2
	v_add_u32_e32 v26, v242, v199
	v_mfma_f32_16x16x32_bf16 v[6:9], v[38:41], v[170:173], v[6:9]
	v_mfma_f32_16x16x32_bf16 v[2:5], v[38:41], v[174:177], v[2:5]
	v_mfma_f32_16x16x32_bf16 v[170:173], v[38:41], v[230:233], v[22:25]
	v_mfma_f32_16x16x32_bf16 v[174:177], v[38:41], v[234:237], v[18:21]
	s_nop 2
	ds_read_b128 v[18:21], v26
	ds_read_b128 v[22:25], v26 offset:8192
	ds_read_b128 v[222:225], v26 offset:16384
	ds_read_b128 v[226:229], v26 offset:24576
	ds_read_b128 v[230:233], v26 offset:32768
	ds_read_b128 v[234:237], v26 offset:40960
	ds_read_b128 v[238:241], v26 offset:49152
	ds_read_b128 v[242:245], v26 offset:57344
	s_waitcnt lgkmcnt(0)
	s_waitcnt vmcnt(0)
	s_waitcnt lgkmcnt(0)
	v_mfma_f32_16x16x32_bf16 v[26:29], v[34:37], v[18:21], v[14:17]
	s_waitcnt lgkmcnt(0)
	s_barrier
	v_mfma_f32_16x16x32_bf16 v[14:17], v[34:37], v[230:233], v[162:165]
	s_nop 2
	v_lshl_add_u64 v[162:163], v[182:183], 0, s[0:1]
	s_mov_b64 s[0:1], 0x22000
	global_load_lds_dwordx4 v[162:163], off nt
	v_lshl_add_u64 v[162:163], v[182:183], 0, s[0:1]
	s_mov_b32 m0, s47
	s_mov_b64 s[0:1], 0x24000
	global_load_lds_dwordx4 v[162:163], off nt
	v_lshl_add_u64 v[162:163], v[182:183], 0, s[0:1]
	s_mov_b32 m0, s24
	s_mov_b64 s[0:1], 0x26000
	global_load_lds_dwordx4 v[162:163], off nt
	v_lshl_add_u64 v[162:163], v[182:183], 0, s[0:1]
	s_mov_b32 m0, s25
	s_mov_b64 s[0:1], 0x28000
	global_load_lds_dwordx4 v[162:163], off nt
	v_lshl_add_u64 v[162:163], v[182:183], 0, s[0:1]
	s_mov_b32 m0, s48
	s_mov_b64 s[0:1], 0x2a000
	global_load_lds_dwordx4 v[162:163], off nt
	v_lshl_add_u64 v[162:163], v[182:183], 0, s[0:1]
	s_mov_b32 m0, s49
	s_mov_b64 s[0:1], 0x2c000
	global_load_lds_dwordx4 v[162:163], off nt
	v_lshl_add_u64 v[162:163], v[182:183], 0, s[0:1]
	s_mov_b32 m0, s50
	s_mov_b64 s[0:1], 0x2e000
	global_load_lds_dwordx4 v[162:163], off nt
	v_lshl_add_u64 v[162:163], v[182:183], 0, s[0:1]
	s_mov_b32 m0, s51
	v_mfma_f32_16x16x32_bf16 v[30:33], v[34:37], v[22:25], v[10:13]
	global_load_lds_dwordx4 v[162:163], off nt
	v_mov_b32_e32 v162, 0x10000
	v_mfma_f32_16x16x32_bf16 v[22:25], v[34:37], v[222:225], v[6:9]
	s_mov_b64 s[0:1], 0x30000
	s_mov_b32 m0, s46
	v_mfma_f32_16x16x32_bf16 v[6:9], v[34:37], v[238:241], v[170:173]
	v_add_u32_e32 v238, 0, v162
	v_mfma_f32_16x16x32_bf16 v[10:13], v[34:37], v[234:237], v[166:169]
	v_add_u32_e32 v234, v238, v192
	v_mfma_f32_16x16x32_bf16 v[18:21], v[34:37], v[226:229], v[2:5]
	v_mfma_f32_16x16x32_bf16 v[2:5], v[34:37], v[242:245], v[174:177]
	ds_read_b128 v[162:165], v234
	ds_read_b128 v[166:169], v234 offset:8192
	ds_read_b128 v[170:173], v234 offset:16384
	ds_read_b128 v[174:177], v234 offset:24576
	ds_read_b128 v[222:225], v234 offset:32768
	ds_read_b128 v[226:229], v234 offset:40960
	ds_read_b128 v[230:233], v234 offset:49152
	ds_read_b128 v[234:237], v234 offset:57344
	s_waitcnt lgkmcnt(0)
; #define LAS __attribute__((address_space(3)))
; #define MFMA16(a, b, c) __builtin_amdgcn_mfma_f32_16x16x32_bf16((a), (b), (c), 0, 0, 0)
; #define WAITV0() asm volatile("s_waitcnt vmcnt(0)" ::: "memory")
; #define LBAR() do { asm volatile("s_waitcnt lgkmcnt(0)" ::: "memory"); __builtin_amdgcn_s_barrier(); asm volatile("" ::: "memory"); } while (0)
; __device__ __forceinline__ void retc_stream(const int wv, LAS unsigned char* lds, unsigned ldsb, const float* __restrict__ gn_g, const float* __restrict__ gn_b, const bf16_t* __restrict__ qkvr, const bf16_t* __restrict__ grb, const bf16_t* __restrict__ kv, ...
;     ...
; #pragma unroll
;         for (int vc = 0; vc < 4; ++vc) {
;             WAITV0(); LBAR();
;             if (vc < 3) RETC_ISSUE(item, 5 + vc);
;             unsigned img = (vc & 1) * 65536u; asm volatile("" : "+v"(img));
; #pragma unroll
;             for (int s = 0; s < 8; ++s) {
;                 bf16x8 bfr[8];
; #pragma unroll
;                 for (int c = 0; c < 8; ++c) bfr[c] = *(const LAS bf16x8*)(lds + img + c * 8192 + koff[s]);
;                 asm volatile("s_waitcnt lgkmcnt(0)" ::: "memory");
; #pragma unroll
;                 for (int c = 0; c < 8; ++c) acc[vc * 8 + c] = MFMA16(qf[s], bfr[c], acc[vc * 8 + c]);
;             }
;         }
	s_waitcnt lgkmcnt(0)
	v_mfma_f32_16x16x32_bf16 v[82:85], v[62:65], v[234:237], v[82:85]
	v_add_u32_e32 v234, v238, v193
	v_mfma_f32_16x16x32_bf16 v[78:81], v[62:65], v[162:165], v[78:81]
	v_mfma_f32_16x16x32_bf16 v[74:77], v[62:65], v[166:169], v[74:77]
	v_mfma_f32_16x16x32_bf16 v[70:73], v[62:65], v[170:173], v[70:73]
	v_mfma_f32_16x16x32_bf16 v[66:69], v[62:65], v[174:177], v[66:69]
	v_mfma_f32_16x16x32_bf16 v[94:97], v[62:65], v[222:225], v[94:97]
	v_mfma_f32_16x16x32_bf16 v[90:93], v[62:65], v[226:229], v[90:93]
	v_mfma_f32_16x16x32_bf16 v[86:89], v[62:65], v[230:233], v[86:89]
	ds_read_b128 v[162:165], v234
	ds_read_b128 v[166:169], v234 offset:8192
	ds_read_b128 v[170:173], v234 offset:16384
	ds_read_b128 v[174:177], v234 offset:24576
	ds_read_b128 v[222:225], v234 offset:32768
	ds_read_b128 v[226:229], v234 offset:40960
	ds_read_b128 v[230:233], v234 offset:49152
	ds_read_b128 v[234:237], v234 offset:57344
	s_waitcnt lgkmcnt(0)
	s_waitcnt lgkmcnt(0)
	v_mfma_f32_16x16x32_bf16 v[82:85], v[58:61], v[234:237], v[82:85]
	v_add_u32_e32 v234, v238, v194
	v_mfma_f32_16x16x32_bf16 v[78:81], v[58:61], v[162:165], v[78:81]
	v_mfma_f32_16x16x32_bf16 v[74:77], v[58:61], v[166:169], v[74:77]
	v_mfma_f32_16x16x32_bf16 v[70:73], v[58:61], v[170:173], v[70:73]
	v_mfma_f32_16x16x32_bf16 v[66:69], v[58:61], v[174:177], v[66:69]
	v_mfma_f32_16x16x32_bf16 v[94:97], v[58:61], v[222:225], v[94:97]
	v_mfma_f32_16x16x32_bf16 v[90:93], v[58:61], v[226:229], v[90:93]
	v_mfma_f32_16x16x32_bf16 v[86:89], v[58:61], v[230:233], v[86:89]
	ds_read_b128 v[162:165], v234
	ds_read_b128 v[166:169], v234 offset:8192
	ds_read_b128 v[170:173], v234 offset:16384
	ds_read_b128 v[174:177], v234 offset:24576
	ds_read_b128 v[222:225], v234 offset:32768
	ds_read_b128 v[226:229], v234 offset:40960
	ds_read_b128 v[230:233], v234 offset:49152
	ds_read_b128 v[234:237], v234 offset:57344
	s_waitcnt lgkmcnt(0)
	s_waitcnt lgkmcnt(0)
	v_mfma_f32_16x16x32_bf16 v[82:85], v[54:57], v[234:237], v[82:85]
	v_add_u32_e32 v234, v238, v195
	v_mfma_f32_16x16x32_bf16 v[78:81], v[54:57], v[162:165], v[78:81]
	v_mfma_f32_16x16x32_bf16 v[74:77], v[54:57], v[166:169], v[74:77]
	v_mfma_f32_16x16x32_bf16 v[70:73], v[54:57], v[170:173], v[70:73]
	v_mfma_f32_16x16x32_bf16 v[66:69], v[54:57], v[174:177], v[66:69]
	v_mfma_f32_16x16x32_bf16 v[94:97], v[54:57], v[222:225], v[94:97]
	v_mfma_f32_16x16x32_bf16 v[90:93], v[54:57], v[226:229], v[90:93]
	v_mfma_f32_16x16x32_bf16 v[86:89], v[54:57], v[230:233], v[86:89]
	ds_read_b128 v[162:165], v234
	ds_read_b128 v[166:169], v234 offset:8192
	ds_read_b128 v[170:173], v234 offset:16384
	ds_read_b128 v[174:177], v234 offset:24576
	ds_read_b128 v[222:225], v234 offset:32768
	ds_read_b128 v[226:229], v234 offset:40960
	ds_read_b128 v[230:233], v234 offset:49152
	ds_read_b128 v[234:237], v234 offset:57344
	s_waitcnt lgkmcnt(0)
	s_waitcnt lgkmcnt(0)
	v_mfma_f32_16x16x32_bf16 v[82:85], v[50:53], v[234:237], v[82:85]
	v_add_u32_e32 v234, v238, v196
	v_mfma_f32_16x16x32_bf16 v[78:81], v[50:53], v[162:165], v[78:81]
	v_mfma_f32_16x16x32_bf16 v[74:77], v[50:53], v[166:169], v[74:77]
	v_mfma_f32_16x16x32_bf16 v[70:73], v[50:53], v[170:173], v[70:73]
	v_mfma_f32_16x16x32_bf16 v[66:69], v[50:53], v[174:177], v[66:69]
	v_mfma_f32_16x16x32_bf16 v[94:97], v[50:53], v[222:225], v[94:97]
	v_mfma_f32_16x16x32_bf16 v[90:93], v[50:53], v[226:229], v[90:93]
	v_mfma_f32_16x16x32_bf16 v[86:89], v[50:53], v[230:233], v[86:89]
	ds_read_b128 v[162:165], v234
	ds_read_b128 v[166:169], v234 offset:8192
	ds_read_b128 v[170:173], v234 offset:16384
	ds_read_b128 v[174:177], v234 offset:24576
	ds_read_b128 v[222:225], v234 offset:32768
	ds_read_b128 v[226:229], v234 offset:40960
	ds_read_b128 v[230:233], v234 offset:49152
	ds_read_b128 v[234:237], v234 offset:57344
	s_waitcnt lgkmcnt(0)
	s_waitcnt lgkmcnt(0)
	v_mfma_f32_16x16x32_bf16 v[82:85], v[46:49], v[234:237], v[82:85]
	v_add_u32_e32 v234, v238, v197
	v_mfma_f32_16x16x32_bf16 v[78:81], v[46:49], v[162:165], v[78:81]
	v_mfma_f32_16x16x32_bf16 v[74:77], v[46:49], v[166:169], v[74:77]
	v_mfma_f32_16x16x32_bf16 v[70:73], v[46:49], v[170:173], v[70:73]
	v_mfma_f32_16x16x32_bf16 v[66:69], v[46:49], v[174:177], v[66:69]
	v_mfma_f32_16x16x32_bf16 v[94:97], v[46:49], v[222:225], v[94:97]
	v_mfma_f32_16x16x32_bf16 v[90:93], v[46:49], v[226:229], v[90:93]
	v_mfma_f32_16x16x32_bf16 v[86:89], v[46:49], v[230:233], v[86:89]
	ds_read_b128 v[162:165], v234
	ds_read_b128 v[166:169], v234 offset:8192
	ds_read_b128 v[170:173], v234 offset:16384
	ds_read_b128 v[174:177], v234 offset:24576
	ds_read_b128 v[222:225], v234 offset:32768
	ds_read_b128 v[226:229], v234 offset:40960
	ds_read_b128 v[230:233], v234 offset:49152
	ds_read_b128 v[234:237], v234 offset:57344
	s_waitcnt lgkmcnt(0)
	s_waitcnt lgkmcnt(0)
	v_mfma_f32_16x16x32_bf16 v[78:81], v[42:45], v[162:165], v[78:81]
	v_mfma_f32_16x16x32_bf16 v[94:97], v[42:45], v[222:225], v[94:97]
	v_mfma_f32_16x16x32_bf16 v[82:85], v[42:45], v[234:237], v[82:85]
	v_add_u32_e32 v234, v238, v198
	v_mfma_f32_16x16x32_bf16 v[74:77], v[42:45], v[166:169], v[74:77]
	v_mfma_f32_16x16x32_bf16 v[70:73], v[42:45], v[170:173], v[70:73]
	v_mfma_f32_16x16x32_bf16 v[66:69], v[42:45], v[174:177], v[66:69]
	v_mfma_f32_16x16x32_bf16 v[90:93], v[42:45], v[226:229], v[90:93]
	v_mfma_f32_16x16x32_bf16 v[86:89], v[42:45], v[230:233], v[86:89]
	ds_read_b128 v[162:165], v234
	ds_read_b128 v[166:169], v234 offset:8192
	ds_read_b128 v[170:173], v234 offset:16384
	ds_read_b128 v[174:177], v234 offset:24576
	ds_read_b128 v[222:225], v234 offset:32768
	ds_read_b128 v[226:229], v234 offset:40960
	ds_read_b128 v[230:233], v234 offset:49152
	ds_read_b128 v[234:237], v234 offset:57344
	s_waitcnt lgkmcnt(0)
	s_waitcnt lgkmcnt(0)
	v_mfma_f32_16x16x32_bf16 v[78:81], v[38:41], v[162:165], v[78:81]
	v_mfma_f32_16x16x32_bf16 v[162:165], v[38:41], v[222:225], v[94:97]
	v_mfma_f32_16x16x32_bf16 v[74:77], v[38:41], v[166:169], v[74:77]
	v_mfma_f32_16x16x32_bf16 v[166:169], v[38:41], v[226:229], v[90:93]
	s_nop 2
	v_add_u32_e32 v90, v238, v199
	v_mfma_f32_16x16x32_bf16 v[70:73], v[38:41], v[170:173], v[70:73]
	v_mfma_f32_16x16x32_bf16 v[66:69], v[38:41], v[174:177], v[66:69]
	v_mfma_f32_16x16x32_bf16 v[170:173], v[38:41], v[230:233], v[86:89]
	v_mfma_f32_16x16x32_bf16 v[174:177], v[38:41], v[234:237], v[82:85]
	s_nop 2
	ds_read_b128 v[82:85], v90
	ds_read_b128 v[86:89], v90 offset:8192
	ds_read_b128 v[222:225], v90 offset:16384
	ds_read_b128 v[226:229], v90 offset:24576
	ds_read_b128 v[230:233], v90 offset:32768
	ds_read_b128 v[234:237], v90 offset:40960
	ds_read_b128 v[238:241], v90 offset:49152
	ds_read_b128 v[242:245], v90 offset:57344
	s_waitcnt lgkmcnt(0)
	s_waitcnt vmcnt(0)
	s_waitcnt lgkmcnt(0)
	v_mfma_f32_16x16x32_bf16 v[94:97], v[34:37], v[82:85], v[78:81]
	s_waitcnt lgkmcnt(0)
	s_barrier
; #define LAS __attribute__((address_space(3)))
; #define MFMA16(a, b, c) __builtin_amdgcn_mfma_f32_16x16x32_bf16((a), (b), (c), 0, 0, 0)
; #define WAITV0() asm volatile("s_waitcnt vmcnt(0)" ::: "memory")
; #define LBAR() do { asm volatile("s_waitcnt lgkmcnt(0)" ::: "memory"); __builtin_amdgcn_s_barrier(); asm volatile("" ::: "memory"); } while (0)
; __device__ __forceinline__ void retc_stream(const int wv, LAS unsigned char* lds, unsigned ldsb, const float* __restrict__ gn_g, const float* __restrict__ gn_b, const bf16_t* __restrict__ qkvr, const bf16_t* __restrict__ grb, const bf16_t* __restrict__ kv, ...
;     ...
; #pragma unroll
;         for (int vc = 0; vc < 4; ++vc) {
;             WAITV0(); LBAR();
;             if (vc < 3) RETC_ISSUE(item, 5 + vc);
;             unsigned img = (vc & 1) * 65536u; asm volatile("" : "+v"(img));
; #pragma unroll
;             for (int s = 0; s < 8; ++s) {
;                 bf16x8 bfr[8];
; #pragma unroll
;                 for (int c = 0; c < 8; ++c) bfr[c] = *(const LAS bf16x8*)(lds + img + c * 8192 + koff[s]);
;                 asm volatile("s_waitcnt lgkmcnt(0)" ::: "memory");
; #pragma unroll
;                 for (int c = 0; c < 8; ++c) acc[vc * 8 + c] = MFMA16(qf[s], bfr[c], acc[vc * 8 + c]);
;             }
;         }
	v_mfma_f32_16x16x32_bf16 v[78:81], v[34:37], v[230:233], v[162:165]
	s_nop 2
	v_lshl_add_u64 v[162:163], v[182:183], 0, s[0:1]
	s_mov_b64 s[0:1], 0x32000
	global_load_lds_dwordx4 v[162:163], off nt
	v_lshl_add_u64 v[162:163], v[182:183], 0, s[0:1]
	s_mov_b32 m0, s53
	s_mov_b64 s[0:1], 0x34000
	global_load_lds_dwordx4 v[162:163], off nt
	v_lshl_add_u64 v[162:163], v[182:183], 0, s[0:1]
	s_mov_b32 m0, s52
	s_mov_b64 s[0:1], 0x36000
	global_load_lds_dwordx4 v[162:163], off nt
	v_lshl_add_u64 v[162:163], v[182:183], 0, s[0:1]
	s_mov_b32 m0, s55
	s_mov_b64 s[0:1], 0x38000
	global_load_lds_dwordx4 v[162:163], off nt
	v_lshl_add_u64 v[162:163], v[182:183], 0, s[0:1]
	s_mov_b32 m0, s54
	s_mov_b64 s[0:1], 0x3a000
	global_load_lds_dwordx4 v[162:163], off nt
	v_lshl_add_u64 v[162:163], v[182:183], 0, s[0:1]
	s_mov_b32 m0, s57
	s_mov_b64 s[0:1], 0x3c000
	global_load_lds_dwordx4 v[162:163], off nt
	v_lshl_add_u64 v[162:163], v[182:183], 0, s[0:1]
	s_mov_b32 m0, s56
	s_mov_b64 s[0:1], 0x3e000
	global_load_lds_dwordx4 v[162:163], off nt
	v_lshl_add_u64 v[162:163], v[182:183], 0, s[0:1]
	s_mov_b32 m0, s59
	v_mfma_f32_16x16x32_bf16 v[90:93], v[34:37], v[86:89], v[74:77]
	global_load_lds_dwordx4 v[162:163], off nt
	v_mov_b32_e32 v162, v0
	v_mfma_f32_16x16x32_bf16 v[86:89], v[34:37], v[222:225], v[70:73]
	s_mov_b32 s0, 0x358637bd
	v_mfma_f32_16x16x32_bf16 v[70:73], v[34:37], v[238:241], v[170:173]
	v_add_u32_e32 v238, 0, v162
	v_mfma_f32_16x16x32_bf16 v[74:77], v[34:37], v[234:237], v[166:169]
	v_add_u32_e32 v234, v238, v192
	v_mfma_f32_16x16x32_bf16 v[82:85], v[34:37], v[226:229], v[66:69]
	v_mfma_f32_16x16x32_bf16 v[66:69], v[34:37], v[242:245], v[174:177]
	ds_read_b128 v[162:165], v234
	ds_read_b128 v[166:169], v234 offset:8192
	ds_read_b128 v[170:173], v234 offset:16384
	ds_read_b128 v[174:177], v234 offset:24576
	ds_read_b128 v[222:225], v234 offset:32768
	ds_read_b128 v[226:229], v234 offset:40960
	ds_read_b128 v[230:233], v234 offset:49152
	ds_read_b128 v[234:237], v234 offset:57344
	s_waitcnt lgkmcnt(0)
	s_waitcnt lgkmcnt(0)
	v_mfma_f32_16x16x32_bf16 v[114:117], v[62:65], v[234:237], v[114:117]
	v_add_u32_e32 v234, v238, v193
	v_mfma_f32_16x16x32_bf16 v[110:113], v[62:65], v[162:165], v[110:113]
	v_mfma_f32_16x16x32_bf16 v[106:109], v[62:65], v[166:169], v[106:109]
	v_mfma_f32_16x16x32_bf16 v[102:105], v[62:65], v[170:173], v[102:105]
	v_mfma_f32_16x16x32_bf16 v[98:101], v[62:65], v[174:177], v[98:101]
	v_mfma_f32_16x16x32_bf16 v[126:129], v[62:65], v[222:225], v[126:129]
	v_mfma_f32_16x16x32_bf16 v[122:125], v[62:65], v[226:229], v[122:125]
	v_mfma_f32_16x16x32_bf16 v[118:121], v[62:65], v[230:233], v[118:121]
	ds_read_b128 v[162:165], v234
	ds_read_b128 v[166:169], v234 offset:8192
	ds_read_b128 v[170:173], v234 offset:16384
	ds_read_b128 v[174:177], v234 offset:24576
	ds_read_b128 v[222:225], v234 offset:32768
	ds_read_b128 v[226:229], v234 offset:40960
	ds_read_b128 v[230:233], v234 offset:49152
	ds_read_b128 v[234:237], v234 offset:57344
	s_waitcnt lgkmcnt(0)
	s_waitcnt lgkmcnt(0)
	v_mfma_f32_16x16x32_bf16 v[114:117], v[58:61], v[234:237], v[114:117]
	v_add_u32_e32 v234, v238, v194
	v_mfma_f32_16x16x32_bf16 v[110:113], v[58:61], v[162:165], v[110:113]
	v_mfma_f32_16x16x32_bf16 v[106:109], v[58:61], v[166:169], v[106:109]
	v_mfma_f32_16x16x32_bf16 v[102:105], v[58:61], v[170:173], v[102:105]
	v_mfma_f32_16x16x32_bf16 v[98:101], v[58:61], v[174:177], v[98:101]
	v_mfma_f32_16x16x32_bf16 v[126:129], v[58:61], v[222:225], v[126:129]
	v_mfma_f32_16x16x32_bf16 v[122:125], v[58:61], v[226:229], v[122:125]
	v_mfma_f32_16x16x32_bf16 v[118:121], v[58:61], v[230:233], v[118:121]
	ds_read_b128 v[162:165], v234
	ds_read_b128 v[166:169], v234 offset:8192
	ds_read_b128 v[170:173], v234 offset:16384
	ds_read_b128 v[174:177], v234 offset:24576
	ds_read_b128 v[222:225], v234 offset:32768
	ds_read_b128 v[226:229], v234 offset:40960
	ds_read_b128 v[230:233], v234 offset:49152
	ds_read_b128 v[234:237], v234 offset:57344
	s_waitcnt lgkmcnt(0)
	s_waitcnt lgkmcnt(0)
	v_mfma_f32_16x16x32_bf16 v[114:117], v[54:57], v[234:237], v[114:117]
	v_add_u32_e32 v234, v238, v195
	v_mfma_f32_16x16x32_bf16 v[110:113], v[54:57], v[162:165], v[110:113]
	v_mfma_f32_16x16x32_bf16 v[106:109], v[54:57], v[166:169], v[106:109]
	v_mfma_f32_16x16x32_bf16 v[102:105], v[54:57], v[170:173], v[102:105]
	v_mfma_f32_16x16x32_bf16 v[98:101], v[54:57], v[174:177], v[98:101]
	v_mfma_f32_16x16x32_bf16 v[126:129], v[54:57], v[222:225], v[126:129]
	v_mfma_f32_16x16x32_bf16 v[122:125], v[54:57], v[226:229], v[122:125]
	v_mfma_f32_16x16x32_bf16 v[118:121], v[54:57], v[230:233], v[118:121]
	ds_read_b128 v[162:165], v234
	ds_read_b128 v[166:169], v234 offset:8192
	ds_read_b128 v[170:173], v234 offset:16384
	ds_read_b128 v[174:177], v234 offset:24576
	ds_read_b128 v[222:225], v234 offset:32768
	ds_read_b128 v[226:229], v234 offset:40960
	ds_read_b128 v[230:233], v234 offset:49152
	ds_read_b128 v[234:237], v234 offset:57344
	s_waitcnt lgkmcnt(0)
	s_waitcnt lgkmcnt(0)
	v_mfma_f32_16x16x32_bf16 v[114:117], v[50:53], v[234:237], v[114:117]
	v_add_u32_e32 v234, v238, v196
	v_mfma_f32_16x16x32_bf16 v[110:113], v[50:53], v[162:165], v[110:113]
	v_mfma_f32_16x16x32_bf16 v[106:109], v[50:53], v[166:169], v[106:109]
	v_mfma_f32_16x16x32_bf16 v[102:105], v[50:53], v[170:173], v[102:105]
	v_mfma_f32_16x16x32_bf16 v[98:101], v[50:53], v[174:177], v[98:101]
	v_mfma_f32_16x16x32_bf16 v[126:129], v[50:53], v[222:225], v[126:129]
	v_mfma_f32_16x16x32_bf16 v[122:125], v[50:53], v[226:229], v[122:125]
	v_mfma_f32_16x16x32_bf16 v[118:121], v[50:53], v[230:233], v[118:121]
	ds_read_b128 v[162:165], v234
	ds_read_b128 v[166:169], v234 offset:8192
	ds_read_b128 v[170:173], v234 offset:16384
	ds_read_b128 v[174:177], v234 offset:24576
	ds_read_b128 v[222:225], v234 offset:32768
	ds_read_b128 v[226:229], v234 offset:40960
	ds_read_b128 v[230:233], v234 offset:49152
	ds_read_b128 v[234:237], v234 offset:57344
	s_waitcnt lgkmcnt(0)
; #define LAS __attribute__((address_space(3)))
; #define MFMA16(a, b, c) __builtin_amdgcn_mfma_f32_16x16x32_bf16((a), (b), (c), 0, 0, 0)
; #define WAITV0() asm volatile("s_waitcnt vmcnt(0)" ::: "memory")
; #define LBAR() do { asm volatile("s_waitcnt lgkmcnt(0)" ::: "memory"); __builtin_amdgcn_s_barrier(); asm volatile("" ::: "memory"); } while (0)
; __device__ __forceinline__ void retc_stream(const int wv, LAS unsigned char* lds, unsigned ldsb, const float* __restrict__ gn_g, const float* __restrict__ gn_b, const bf16_t* __restrict__ qkvr, const bf16_t* __restrict__ grb, const bf16_t* __restrict__ kv, ...
;     ...
; #pragma unroll
;         for (int vc = 0; vc < 4; ++vc) {
;             WAITV0(); LBAR();
;             if (vc < 3) RETC_ISSUE(item, 5 + vc);
;             unsigned img = (vc & 1) * 65536u; asm volatile("" : "+v"(img));
; #pragma unroll
;             for (int s = 0; s < 8; ++s) {
;                 bf16x8 bfr[8];
; #pragma unroll
;                 for (int c = 0; c < 8; ++c) bfr[c] = *(const LAS bf16x8*)(lds + img + c * 8192 + koff[s]);
;                 asm volatile("s_waitcnt lgkmcnt(0)" ::: "memory");
; #pragma unroll
;                 for (int c = 0; c < 8; ++c) acc[vc * 8 + c] = MFMA16(qf[s], bfr[c], acc[vc * 8 + c]);
;             }
;         }
	s_waitcnt lgkmcnt(0)
	v_mfma_f32_16x16x32_bf16 v[114:117], v[46:49], v[234:237], v[114:117]
	v_add_u32_e32 v234, v238, v197
	v_mfma_f32_16x16x32_bf16 v[110:113], v[46:49], v[162:165], v[110:113]
	v_mfma_f32_16x16x32_bf16 v[106:109], v[46:49], v[166:169], v[106:109]
	v_mfma_f32_16x16x32_bf16 v[102:105], v[46:49], v[170:173], v[102:105]
	v_mfma_f32_16x16x32_bf16 v[98:101], v[46:49], v[174:177], v[98:101]
	v_mfma_f32_16x16x32_bf16 v[126:129], v[46:49], v[222:225], v[126:129]
	v_mfma_f32_16x16x32_bf16 v[122:125], v[46:49], v[226:229], v[122:125]
	v_mfma_f32_16x16x32_bf16 v[118:121], v[46:49], v[230:233], v[118:121]
	ds_read_b128 v[162:165], v234
	ds_read_b128 v[166:169], v234 offset:8192
	ds_read_b128 v[170:173], v234 offset:16384
	ds_read_b128 v[174:177], v234 offset:24576
	ds_read_b128 v[222:225], v234 offset:32768
	ds_read_b128 v[226:229], v234 offset:40960
	ds_read_b128 v[230:233], v234 offset:49152
	ds_read_b128 v[234:237], v234 offset:57344
	s_waitcnt lgkmcnt(0)
	s_waitcnt lgkmcnt(0)
	v_mfma_f32_16x16x32_bf16 v[114:117], v[42:45], v[234:237], v[114:117]
	v_add_u32_e32 v234, v238, v198
	v_mfma_f32_16x16x32_bf16 v[110:113], v[42:45], v[162:165], v[110:113]
	v_mfma_f32_16x16x32_bf16 v[106:109], v[42:45], v[166:169], v[106:109]
	v_mfma_f32_16x16x32_bf16 v[102:105], v[42:45], v[170:173], v[102:105]
	v_mfma_f32_16x16x32_bf16 v[98:101], v[42:45], v[174:177], v[98:101]
	v_mfma_f32_16x16x32_bf16 v[126:129], v[42:45], v[222:225], v[126:129]
	v_mfma_f32_16x16x32_bf16 v[122:125], v[42:45], v[226:229], v[122:125]
	v_mfma_f32_16x16x32_bf16 v[118:121], v[42:45], v[230:233], v[118:121]
	ds_read_b128 v[162:165], v234
	ds_read_b128 v[166:169], v234 offset:8192
	ds_read_b128 v[170:173], v234 offset:16384
	ds_read_b128 v[174:177], v234 offset:24576
	ds_read_b128 v[222:225], v234 offset:32768
	ds_read_b128 v[226:229], v234 offset:40960
	ds_read_b128 v[230:233], v234 offset:49152
	ds_read_b128 v[234:237], v234 offset:57344
	s_waitcnt lgkmcnt(0)
	s_waitcnt lgkmcnt(0)
	v_mfma_f32_16x16x32_bf16 v[110:113], v[38:41], v[162:165], v[110:113]
	v_mfma_f32_16x16x32_bf16 v[106:109], v[38:41], v[166:169], v[106:109]
	v_mfma_f32_16x16x32_bf16 v[162:165], v[38:41], v[170:173], v[102:105]
	s_nop 2
	v_add_u32_e32 v102, v238, v199
	v_mfma_f32_16x16x32_bf16 v[166:169], v[38:41], v[174:177], v[98:101]
	v_mfma_f32_16x16x32_bf16 v[170:173], v[38:41], v[222:225], v[126:129]
	v_mfma_f32_16x16x32_bf16 v[174:177], v[38:41], v[226:229], v[122:125]
	v_mfma_f32_16x16x32_bf16 v[222:225], v[38:41], v[230:233], v[118:121]
	v_mfma_f32_16x16x32_bf16 v[226:229], v[38:41], v[234:237], v[114:117]
	ds_read_b128 v[98:101], v102
	s_nop 1
	ds_read_b128 v[114:117], v102 offset:8192
	ds_read_b128 v[118:121], v102 offset:16384
	ds_read_b128 v[122:125], v102 offset:24576
	ds_read_b128 v[230:233], v102 offset:32768
	ds_read_b128 v[234:237], v102 offset:40960
	ds_read_b128 v[238:241], v102 offset:49152
	ds_read_b128 v[242:245], v102 offset:57344
	s_waitcnt lgkmcnt(0)
	s_waitcnt vmcnt(0)
	s_waitcnt lgkmcnt(0)
	v_mfma_f32_16x16x32_bf16 v[102:105], v[34:37], v[98:101], v[110:113]
	s_waitcnt lgkmcnt(0)
	s_barrier
	v_mfma_f32_16x16x32_bf16 v[98:101], v[34:37], v[114:117], v[106:109]
	v_mfma_f32_16x16x32_bf16 v[106:109], v[34:37], v[118:121], v[162:165]
	s_nop 2
	v_mov_b32_e32 v162, 0x10000
	v_mfma_f32_16x16x32_bf16 v[114:117], v[34:37], v[238:241], v[222:225]
	s_nop 0
	v_add_u32_e32 v238, 0, v162
	v_mfma_f32_16x16x32_bf16 v[118:121], v[34:37], v[234:237], v[174:177]
	v_add_u32_e32 v234, v238, v192
	v_mfma_f32_16x16x32_bf16 v[126:129], v[34:37], v[122:125], v[166:169]
	v_mfma_f32_16x16x32_bf16 v[122:125], v[34:37], v[230:233], v[170:173]
	v_mfma_f32_16x16x32_bf16 v[110:113], v[34:37], v[242:245], v[226:229]
	ds_read_b128 v[162:165], v234
	ds_read_b128 v[166:169], v234 offset:8192
	ds_read_b128 v[170:173], v234 offset:16384
	ds_read_b128 v[174:177], v234 offset:24576
	ds_read_b128 v[222:225], v234 offset:32768
	ds_read_b128 v[226:229], v234 offset:40960
	ds_read_b128 v[230:233], v234 offset:49152
	ds_read_b128 v[234:237], v234 offset:57344
	s_waitcnt lgkmcnt(0)
	s_waitcnt lgkmcnt(0)
	v_mfma_f32_16x16x32_bf16 v[150:153], v[62:65], v[230:233], v[150:153]
	v_add_u32_e32 v230, v238, v193
	v_mfma_f32_16x16x32_bf16 v[142:145], v[62:65], v[162:165], v[142:145]
	v_mfma_f32_16x16x32_bf16 v[138:141], v[62:65], v[166:169], v[138:141]
	v_mfma_f32_16x16x32_bf16 v[134:137], v[62:65], v[170:173], v[134:137]
	v_mfma_f32_16x16x32_bf16 v[130:133], v[62:65], v[174:177], v[130:133]
	v_mfma_f32_16x16x32_bf16 v[158:161], v[62:65], v[222:225], v[158:161]
	v_mfma_f32_16x16x32_bf16 v[154:157], v[62:65], v[226:229], v[154:157]
	v_mfma_f32_16x16x32_bf16 v[62:65], v[62:65], v[234:237], v[146:149]
	s_nop 2
	ds_read_b128 v[146:149], v230
	ds_read_b128 v[162:165], v230 offset:8192
	ds_read_b128 v[166:169], v230 offset:16384
	ds_read_b128 v[170:173], v230 offset:24576
	ds_read_b128 v[174:177], v230 offset:32768
	ds_read_b128 v[222:225], v230 offset:40960
	ds_read_b128 v[226:229], v230 offset:49152
	ds_read_b128 v[230:233], v230 offset:57344
	s_waitcnt lgkmcnt(0)
	s_waitcnt lgkmcnt(0)
	v_mfma_f32_16x16x32_bf16 v[150:153], v[58:61], v[226:229], v[150:153]
	v_add_u32_e32 v226, v238, v194
	v_mfma_f32_16x16x32_bf16 v[142:145], v[58:61], v[146:149], v[142:145]
	v_mfma_f32_16x16x32_bf16 v[138:141], v[58:61], v[162:165], v[138:141]
	v_mfma_f32_16x16x32_bf16 v[134:137], v[58:61], v[166:169], v[134:137]
	v_mfma_f32_16x16x32_bf16 v[130:133], v[58:61], v[170:173], v[130:133]
	v_mfma_f32_16x16x32_bf16 v[146:149], v[58:61], v[174:177], v[158:161]
	v_mfma_f32_16x16x32_bf16 v[154:157], v[58:61], v[222:225], v[154:157]
	v_mfma_f32_16x16x32_bf16 v[58:61], v[58:61], v[230:233], v[62:65]
	s_nop 2
	ds_read_b128 v[62:65], v226
	ds_read_b128 v[158:161], v226 offset:8192
	ds_read_b128 v[162:165], v226 offset:16384
	ds_read_b128 v[166:169], v226 offset:24576
	ds_read_b128 v[170:173], v226 offset:32768
	ds_read_b128 v[174:177], v226 offset:40960
	ds_read_b128 v[222:225], v226 offset:49152
	ds_read_b128 v[226:229], v226 offset:57344
	s_waitcnt lgkmcnt(0)
; #define LAS __attribute__((address_space(3)))
; #define MFMA16(a, b, c) __builtin_amdgcn_mfma_f32_16x16x32_bf16((a), (b), (c), 0, 0, 0)
; #define WAITV0() asm volatile("s_waitcnt vmcnt(0)" ::: "memory")
; #define LBAR() do { asm volatile("s_waitcnt lgkmcnt(0)" ::: "memory"); __builtin_amdgcn_s_barrier(); asm volatile("" ::: "memory"); } while (0)
; __device__ __forceinline__ void retc_stream(const int wv, LAS unsigned char* lds, unsigned ldsb, const float* __restrict__ gn_g, const float* __restrict__ gn_b, const bf16_t* __restrict__ qkvr, const bf16_t* __restrict__ grb, const bf16_t* __restrict__ kv, ...
;     ...
;         for (int vc = 0; vc < 4; ++vc) {
;             WAITV0(); LBAR();
;             if (vc < 3) RETC_ISSUE(item, 5 + vc);
;             unsigned img = (vc & 1) * 65536u; asm volatile("" : "+v"(img));
; #pragma unroll
;             for (int s = 0; s < 8; ++s) {
;                 bf16x8 bfr[8];
; #pragma unroll
;                 for (int c = 0; c < 8; ++c) bfr[c] = *(const LAS bf16x8*)(lds + img + c * 8192 + koff[s]);
;                 asm volatile("s_waitcnt lgkmcnt(0)" ::: "memory");
; #pragma unroll
;                 for (int c = 0; c < 8; ++c) acc[vc * 8 + c] = MFMA16(qf[s], bfr[c], acc[vc * 8 + c]);
;             }
;         }
;     ...
;         LBAR();
	s_waitcnt lgkmcnt(0)
	v_mfma_f32_16x16x32_bf16 v[150:153], v[54:57], v[222:225], v[150:153]
	v_add_u32_e32 v222, v238, v195
	v_mfma_f32_16x16x32_bf16 v[62:65], v[54:57], v[62:65], v[142:145]
	v_mfma_f32_16x16x32_bf16 v[138:141], v[54:57], v[158:161], v[138:141]
	v_mfma_f32_16x16x32_bf16 v[134:137], v[54:57], v[162:165], v[134:137]
	v_mfma_f32_16x16x32_bf16 v[130:133], v[54:57], v[166:169], v[130:133]
	v_mfma_f32_16x16x32_bf16 v[142:145], v[54:57], v[170:173], v[146:149]
	v_mfma_f32_16x16x32_bf16 v[146:149], v[54:57], v[174:177], v[154:157]
	v_mfma_f32_16x16x32_bf16 v[54:57], v[54:57], v[226:229], v[58:61]
	s_nop 2
	ds_read_b128 v[58:61], v222
	ds_read_b128 v[154:157], v222 offset:8192
	ds_read_b128 v[158:161], v222 offset:16384
	ds_read_b128 v[162:165], v222 offset:24576
	ds_read_b128 v[166:169], v222 offset:32768
	ds_read_b128 v[170:173], v222 offset:40960
	ds_read_b128 v[174:177], v222 offset:49152
	ds_read_b128 v[222:225], v222 offset:57344
	s_waitcnt lgkmcnt(0)
	s_waitcnt lgkmcnt(0)
	v_mfma_f32_16x16x32_bf16 v[58:61], v[50:53], v[58:61], v[62:65]
	v_mfma_f32_16x16x32_bf16 v[62:65], v[50:53], v[154:157], v[138:141]
	v_mfma_f32_16x16x32_bf16 v[138:141], v[50:53], v[166:169], v[142:145]
	v_mfma_f32_16x16x32_bf16 v[142:145], v[50:53], v[170:173], v[146:149]
	v_mfma_f32_16x16x32_bf16 v[146:149], v[50:53], v[174:177], v[150:153]
	v_add_u32_e32 v174, v238, v196
	v_mfma_f32_16x16x32_bf16 v[134:137], v[50:53], v[158:161], v[134:137]
	v_mfma_f32_16x16x32_bf16 v[130:133], v[50:53], v[162:165], v[130:133]
	v_mfma_f32_16x16x32_bf16 v[50:53], v[50:53], v[222:225], v[54:57]
	s_nop 2
	ds_read_b128 v[54:57], v174
	ds_read_b128 v[150:153], v174 offset:8192
	ds_read_b128 v[154:157], v174 offset:16384
	ds_read_b128 v[158:161], v174 offset:24576
	ds_read_b128 v[162:165], v174 offset:32768
	ds_read_b128 v[166:169], v174 offset:40960
	ds_read_b128 v[170:173], v174 offset:49152
	ds_read_b128 v[174:177], v174 offset:57344
	s_waitcnt lgkmcnt(0)
	s_waitcnt lgkmcnt(0)
	v_mfma_f32_16x16x32_bf16 v[54:57], v[46:49], v[54:57], v[58:61]
	v_mfma_f32_16x16x32_bf16 v[58:61], v[46:49], v[150:153], v[62:65]
	v_mfma_f32_16x16x32_bf16 v[62:65], v[46:49], v[154:157], v[134:137]
	v_mfma_f32_16x16x32_bf16 v[134:137], v[46:49], v[162:165], v[138:141]
	v_mfma_f32_16x16x32_bf16 v[138:141], v[46:49], v[166:169], v[142:145]
	v_mfma_f32_16x16x32_bf16 v[142:145], v[46:49], v[170:173], v[146:149]
	v_add_u32_e32 v170, v238, v197
	v_mfma_f32_16x16x32_bf16 v[130:133], v[46:49], v[158:161], v[130:133]
	v_mfma_f32_16x16x32_bf16 v[46:49], v[46:49], v[174:177], v[50:53]
	s_nop 2
	ds_read_b128 v[50:53], v170
	ds_read_b128 v[146:149], v170 offset:8192
	ds_read_b128 v[150:153], v170 offset:16384
	ds_read_b128 v[154:157], v170 offset:24576
	ds_read_b128 v[158:161], v170 offset:32768
	ds_read_b128 v[162:165], v170 offset:40960
	ds_read_b128 v[166:169], v170 offset:49152
	ds_read_b128 v[170:173], v170 offset:57344
	s_waitcnt lgkmcnt(0)
	s_waitcnt lgkmcnt(0)
	v_mfma_f32_16x16x32_bf16 v[50:53], v[42:45], v[50:53], v[54:57]
	v_mfma_f32_16x16x32_bf16 v[54:57], v[42:45], v[146:149], v[58:61]
	v_mfma_f32_16x16x32_bf16 v[58:61], v[42:45], v[150:153], v[62:65]
	v_mfma_f32_16x16x32_bf16 v[62:65], v[42:45], v[154:157], v[130:133]
	v_mfma_f32_16x16x32_bf16 v[130:133], v[42:45], v[158:161], v[134:137]
	v_mfma_f32_16x16x32_bf16 v[134:137], v[42:45], v[162:165], v[138:141]
	v_mfma_f32_16x16x32_bf16 v[138:141], v[42:45], v[166:169], v[142:145]
	v_add_u32_e32 v166, v238, v198
	v_mfma_f32_16x16x32_bf16 v[42:45], v[42:45], v[170:173], v[46:49]
	s_nop 2
	ds_read_b128 v[46:49], v166
	ds_read_b128 v[142:145], v166 offset:8192
	ds_read_b128 v[146:149], v166 offset:16384
	ds_read_b128 v[150:153], v166 offset:24576
	ds_read_b128 v[154:157], v166 offset:32768
	ds_read_b128 v[158:161], v166 offset:40960
	ds_read_b128 v[162:165], v166 offset:49152
	ds_read_b128 v[166:169], v166 offset:57344
	s_waitcnt lgkmcnt(0)
	s_waitcnt lgkmcnt(0)
	v_mfma_f32_16x16x32_bf16 v[46:49], v[38:41], v[46:49], v[50:53]
	v_mfma_f32_16x16x32_bf16 v[50:53], v[38:41], v[142:145], v[54:57]
	v_mfma_f32_16x16x32_bf16 v[54:57], v[38:41], v[146:149], v[58:61]
	v_mfma_f32_16x16x32_bf16 v[58:61], v[38:41], v[150:153], v[62:65]
	v_mfma_f32_16x16x32_bf16 v[62:65], v[38:41], v[154:157], v[130:133]
	v_mfma_f32_16x16x32_bf16 v[130:133], v[38:41], v[158:161], v[134:137]
	v_mfma_f32_16x16x32_bf16 v[134:137], v[38:41], v[162:165], v[138:141]
	v_add_u32_e32 v162, v238, v199
	v_mfma_f32_16x16x32_bf16 v[138:141], v[38:41], v[166:169], v[42:45]
	ds_read_b128 v[38:41], v162
	s_nop 1
	ds_read_b128 v[42:45], v162 offset:8192
	ds_read_b128 v[142:145], v162 offset:16384
	ds_read_b128 v[146:149], v162 offset:24576
	ds_read_b128 v[150:153], v162 offset:32768
	ds_read_b128 v[154:157], v162 offset:40960
	ds_read_b128 v[158:161], v162 offset:49152
	ds_read_b128 v[162:165], v162 offset:57344
	s_waitcnt lgkmcnt(0)
	s_waitcnt lgkmcnt(0)
	s_waitcnt lgkmcnt(0)
	v_mfma_f32_16x16x32_bf16 v[46:49], v[34:37], v[38:41], v[46:49]
	s_barrier
; #define LAS __attribute__((address_space(3)))
; __device__ __forceinline__ float shx(float v, int lane, int mask) { return __int_as_float(__builtin_amdgcn_ds_bpermute((lane ^ mask) << 2, __float_as_int(v))); }
; #define MFMA16(a, b, c) __builtin_amdgcn_mfma_f32_16x16x32_bf16((a), (b), (c), 0, 0, 0)
; __device__ __forceinline__ void retc_stream(const int wv, LAS unsigned char* lds, unsigned ldsb, const float* __restrict__ gn_g, const float* __restrict__ gn_b, const bf16_t* __restrict__ qkvr, const bf16_t* __restrict__ grb, const bf16_t* __restrict__ kv, ...
;     ...
;             for (int s = 0; s < 8; ++s) {
;                 bf16x8 bfr[8];
; #pragma unroll
;                 for (int c = 0; c < 8; ++c) bfr[c] = *(const LAS bf16x8*)(lds + img + c * 8192 + koff[s]);
;                 asm volatile("s_waitcnt lgkmcnt(0)" ::: "memory");
; #pragma unroll
;                 for (int c = 0; c < 8; ++c) acc[vc * 8 + c] = MFMA16(qf[s], bfr[c], acc[vc * 8 + c]);
;             }
;         }
;         const float* gng = gn_g + h * 512; const float* gnb = gn_b + h * 512;
;         float mu4[4], rs4[4];
; #pragma unroll
;         for (int e = 0; e < 4; ++e) {
;             const int q = 16 * w + 4 * g + e;
;             const float xi = exp2f(lg2 * (float)(q - 127));
;             float sum = 0.f;
; #pragma unroll
;             for (int c = 0; c < 32; ++c) { acc[c][e] *= xi; sum += acc[c][e]; }
;             sum += shx(sum, lane, 1); sum += shx(sum, lane, 2); sum += shx(sum, lane, 4); sum += shx(sum, lane, 8);
	v_mfma_f32_16x16x32_bf16 v[42:45], v[34:37], v[42:45], v[50:53]
	v_mfma_f32_16x16x32_bf16 v[38:41], v[34:37], v[142:145], v[54:57]
	v_mfma_f32_16x16x32_bf16 v[58:61], v[34:37], v[146:149], v[58:61]
	v_mfma_f32_16x16x32_bf16 v[50:53], v[34:37], v[150:153], v[62:65]
	v_mfma_f32_16x16x32_bf16 v[62:65], v[34:37], v[154:157], v[130:133]
	v_mfma_f32_16x16x32_bf16 v[54:57], v[34:37], v[158:161], v[134:137]
	s_nop 1
	v_mul_f32_e32 v130, v1, v213
	v_cmp_gt_f32_e32 vcc, s41, v130
	v_mfma_f32_16x16x32_bf16 v[34:37], v[34:37], v[162:165], v[138:141]
	s_nop 0
	v_cndmask_b32_e32 v130, 0, v187, vcc
	v_cndmask_b32_e32 v131, 0, v189, vcc
	v_fmac_f32_e32 v130, v1, v213
	v_exp_f32_e32 v130, v130
	v_mov_b32_e32 v133, v54
	s_nop 1
	v_mov_b32_e32 v132, v34
	v_mul_f32_e32 v34, v1, v214
	v_cmp_gt_f32_e32 vcc, s41, v34
	v_ldexp_f32 v130, v130, v131
	v_mov_b32_e32 v134, v62
	v_cndmask_b32_e32 v34, 0, v187, vcc
	v_fmac_f32_e32 v34, v1, v214
	v_exp_f32_e32 v34, v34
	v_mov_b32_e32 v135, v50
	v_mov_b32_e32 v136, v58
	v_mov_b32_e32 v137, v38
	v_cndmask_b32_e32 v38, 0, v189, vcc
	v_pk_mul_f32 v[138:139], v[130:131], v[132:133] op_sel_hi:[0,1]
	v_pk_mul_f32 v[140:141], v[130:131], v[134:135] op_sel_hi:[0,1]
	v_pk_mul_f32 v[142:143], v[130:131], v[136:137] op_sel_hi:[0,1]
	v_ldexp_f32 v131, v34, v38
	v_mov_b32_e32 v158, v131
	v_mov_b32_e32 v54, v35
	v_mov_b32_e32 v50, v63
	v_mov_b32_e32 v38, v59
	v_pk_mul_f32 v[34:35], v[158:159], v[54:55] op_sel_hi:[0,1]
	v_pk_mul_f32 v[62:63], v[158:159], v[50:51] op_sel_hi:[0,1]
	v_pk_mul_f32 v[58:59], v[158:159], v[38:39] op_sel_hi:[0,1]
	v_mov_b32_e32 v144, v139
	v_mov_b32_e32 v145, v35
	v_mov_b32_e32 v139, v34
	v_mov_b32_e32 v34, v143
	v_mov_b32_e32 v35, v59
	v_mov_b32_e32 v143, v58
	v_mov_b32_e32 v58, v141
	v_mov_b32_e32 v59, v63
	v_mov_b32_e32 v141, v62
	v_pk_fma_f32 v[62:63], v[130:131], v[26:27], 0 op_sel_hi:[1,1,0]
	s_nop 0
	v_pk_fma_f32 v[62:63], v[130:131], v[30:31], v[62:63]
	s_nop 0
	v_pk_fma_f32 v[62:63], v[130:131], v[22:23], v[62:63]
	s_nop 0
	v_pk_fma_f32 v[62:63], v[130:131], v[18:19], v[62:63]
	s_nop 0
	v_pk_fma_f32 v[62:63], v[130:131], v[14:15], v[62:63]
	s_nop 0
	v_pk_fma_f32 v[62:63], v[130:131], v[10:11], v[62:63]
	s_nop 0
	v_pk_fma_f32 v[62:63], v[130:131], v[6:7], v[62:63]
	s_nop 0
	v_pk_fma_f32 v[62:63], v[130:131], v[2:3], v[62:63]
	s_nop 0
	v_pk_fma_f32 v[62:63], v[130:131], v[94:95], v[62:63]
	s_nop 0
	v_pk_fma_f32 v[62:63], v[130:131], v[90:91], v[62:63]
	s_nop 0
	v_pk_fma_f32 v[62:63], v[130:131], v[86:87], v[62:63]
	s_nop 0
	v_pk_fma_f32 v[62:63], v[130:131], v[82:83], v[62:63]
	s_nop 0
	v_pk_fma_f32 v[62:63], v[130:131], v[78:79], v[62:63]
	s_nop 0
	v_pk_fma_f32 v[62:63], v[130:131], v[74:75], v[62:63]
	s_nop 0
	v_pk_fma_f32 v[62:63], v[130:131], v[70:71], v[62:63]
	s_nop 0
	v_pk_fma_f32 v[62:63], v[130:131], v[66:67], v[62:63]
	s_nop 0
	v_pk_fma_f32 v[62:63], v[130:131], v[102:103], v[62:63]
	s_nop 0
	v_pk_fma_f32 v[62:63], v[130:131], v[98:99], v[62:63]
	s_nop 0
	v_pk_fma_f32 v[62:63], v[130:131], v[106:107], v[62:63]
	s_nop 0
	v_pk_fma_f32 v[62:63], v[130:131], v[126:127], v[62:63]
	s_nop 0
	v_pk_fma_f32 v[62:63], v[130:131], v[122:123], v[62:63]
	s_nop 0
	v_pk_fma_f32 v[62:63], v[130:131], v[118:119], v[62:63]
	s_nop 0
	v_pk_fma_f32 v[62:63], v[130:131], v[114:115], v[62:63]
	s_nop 0
	v_pk_fma_f32 v[62:63], v[130:131], v[110:111], v[62:63]
	s_nop 0
	v_pk_fma_f32 v[62:63], v[130:131], v[46:47], v[62:63]
	s_nop 0
	v_pk_fma_f32 v[62:63], v[130:131], v[42:43], v[62:63]
	s_nop 0
	v_pk_add_f32 v[34:35], v[62:63], v[34:35]
	s_nop 0
	v_pk_add_f32 v[34:35], v[34:35], v[142:143]
	s_nop 0
	v_pk_add_f32 v[34:35], v[34:35], v[58:59]
	s_nop 0
	v_pk_add_f32 v[34:35], v[34:35], v[140:141]
	s_nop 0
	v_pk_add_f32 v[34:35], v[34:35], v[144:145]
	s_nop 0
	v_pk_add_f32 v[34:35], v[34:35], v[138:139]
	s_waitcnt lgkmcnt(0)
	s_nop 1
	v_add_f32_dpp v34, v34, v34 quad_perm:[1,0,3,2] row_mask:0xf bank_mask:0xf
	v_add_f32_dpp v35, v35, v35 quad_perm:[1,0,3,2] row_mask:0xf bank_mask:0xf
	s_waitcnt lgkmcnt(0)
	s_nop 1
	v_add_f32_dpp v34, v34, v34 quad_perm:[2,3,0,1] row_mask:0xf bank_mask:0xf
	v_add_f32_dpp v35, v35, v35 quad_perm:[2,3,0,1] row_mask:0xf bank_mask:0xf
	s_waitcnt lgkmcnt(0)
	s_nop 1
	v_add_f32_dpp v34, v34, v34 row_half_mirror row_mask:0xf bank_mask:0xf
	v_add_f32_dpp v35, v35, v35 row_half_mirror row_mask:0xf bank_mask:0xf
	s_waitcnt lgkmcnt(0)
; __device__ __forceinline__ float shx(float v, int lane, int mask) { return __int_as_float(__builtin_amdgcn_ds_bpermute((lane ^ mask) << 2, __float_as_int(v))); }
; __device__ __forceinline__ void retc_stream(const int wv, LAS unsigned char* lds, unsigned ldsb, const float* __restrict__ gn_g, const float* __restrict__ gn_b, const bf16_t* __restrict__ qkvr, const bf16_t* __restrict__ grb, const bf16_t* __restrict__ kv, ...
;     ...
;             for (int c = 0; c < 32; ++c) { acc[c][e] *= xi; sum += acc[c][e]; }
;             sum += shx(sum, lane, 1); sum += shx(sum, lane, 2); sum += shx(sum, lane, 4); sum += shx(sum, lane, 8);
;             const float mu = sum * (1.0f / 512.0f);
;             float var = 0.f;
; #pragma unroll
;             for (int c = 0; c < 32; ++c) { const float d = acc[c][e] - mu; var += d * d; }
;             var += shx(var, lane, 1); var += shx(var, lane, 2); var += shx(var, lane, 4); var += shx(var, lane, 8);
;             mu4[e] = mu; rs4[e] = rsqrtf(var * (1.0f / 512.0f) + EPS);
	s_nop 1
	v_add_f32_dpp v34, v34, v34 row_mirror row_mask:0xf bank_mask:0xf
	v_add_f32_dpp v35, v35, v35 row_mirror row_mask:0xf bank_mask:0xf
	s_nop 0
	v_pk_mul_f32 v[160:161], v[34:35], s[40:41] op_sel_hi:[1,0]
	s_nop 0
	v_pk_fma_f32 v[154:155], v[130:131], v[30:31], v[160:161] neg_lo:[0,0,1] neg_hi:[0,0,1]
	v_pk_fma_f32 v[156:157], v[130:131], v[26:27], v[160:161] neg_lo:[0,0,1] neg_hi:[0,0,1]
	v_pk_mul_f32 v[26:27], v[154:155], v[154:155]
	v_pk_fma_f32 v[152:153], v[130:131], v[22:23], v[160:161] neg_lo:[0,0,1] neg_hi:[0,0,1]
	v_pk_fma_f32 v[26:27], v[156:157], v[156:157], v[26:27]
	v_pk_fma_f32 v[150:151], v[130:131], v[18:19], v[160:161] neg_lo:[0,0,1] neg_hi:[0,0,1]
	v_pk_fma_f32 v[22:23], v[152:153], v[152:153], v[26:27]
	v_pk_fma_f32 v[148:149], v[130:131], v[14:15], v[160:161] neg_lo:[0,0,1] neg_hi:[0,0,1]
	v_pk_fma_f32 v[18:19], v[150:151], v[150:151], v[22:23]
	v_pk_fma_f32 v[146:147], v[130:131], v[10:11], v[160:161] neg_lo:[0,0,1] neg_hi:[0,0,1]
	v_pk_fma_f32 v[14:15], v[148:149], v[148:149], v[18:19]
	v_pk_fma_f32 v[144:145], v[130:131], v[6:7], v[160:161] neg_lo:[0,0,1] neg_hi:[0,0,1]
	v_pk_fma_f32 v[10:11], v[146:147], v[146:147], v[14:15]
	v_pk_fma_f32 v[142:143], v[130:131], v[2:3], v[160:161] neg_lo:[0,0,1] neg_hi:[0,0,1]
	v_pk_fma_f32 v[6:7], v[144:145], v[144:145], v[10:11]
	v_pk_fma_f32 v[140:141], v[130:131], v[94:95], v[160:161] neg_lo:[0,0,1] neg_hi:[0,0,1]
	v_pk_fma_f32 v[2:3], v[142:143], v[142:143], v[6:7]
	v_pk_fma_f32 v[138:139], v[130:131], v[90:91], v[160:161] neg_lo:[0,0,1] neg_hi:[0,0,1]
	v_pk_fma_f32 v[2:3], v[140:141], v[140:141], v[2:3]
	v_pk_fma_f32 v[62:63], v[130:131], v[136:137], v[160:161] op_sel_hi:[0,1,0] neg_lo:[0,0,1] neg_hi:[0,0,1]
	v_pk_fma_f32 v[2:3], v[138:139], v[138:139], v[2:3]
	v_pk_fma_f32 v[136:137], v[130:131], v[86:87], v[160:161] neg_lo:[0,0,1] neg_hi:[0,0,1]
	v_pk_fma_f32 v[58:59], v[130:131], v[134:135], v[160:161] op_sel_hi:[0,1,0] neg_lo:[0,0,1] neg_hi:[0,0,1]
	v_pk_fma_f32 v[2:3], v[136:137], v[136:137], v[2:3]
	v_pk_fma_f32 v[134:135], v[130:131], v[82:83], v[160:161] neg_lo:[0,0,1] neg_hi:[0,0,1]
	v_pk_fma_f32 v[34:35], v[130:131], v[132:133], v[160:161] op_sel_hi:[0,1,0] neg_lo:[0,0,1] neg_hi:[0,0,1]
	v_pk_fma_f32 v[2:3], v[134:135], v[134:135], v[2:3]
	v_pk_fma_f32 v[132:133], v[130:131], v[78:79], v[160:161] neg_lo:[0,0,1] neg_hi:[0,0,1]
	v_pk_fma_f32 v[94:95], v[130:131], v[74:75], v[160:161] neg_lo:[0,0,1] neg_hi:[0,0,1]
	v_pk_fma_f32 v[2:3], v[132:133], v[132:133], v[2:3]
	v_pk_fma_f32 v[90:91], v[130:131], v[70:71], v[160:161] neg_lo:[0,0,1] neg_hi:[0,0,1]
	v_pk_fma_f32 v[2:3], v[94:95], v[94:95], v[2:3]
	v_pk_fma_f32 v[86:87], v[130:131], v[66:67], v[160:161] neg_lo:[0,0,1] neg_hi:[0,0,1]
	v_pk_fma_f32 v[2:3], v[90:91], v[90:91], v[2:3]
	v_pk_fma_f32 v[82:83], v[130:131], v[102:103], v[160:161] neg_lo:[0,0,1] neg_hi:[0,0,1]
	v_pk_fma_f32 v[2:3], v[86:87], v[86:87], v[2:3]
	v_pk_fma_f32 v[78:79], v[130:131], v[98:99], v[160:161] neg_lo:[0,0,1] neg_hi:[0,0,1]
	v_pk_fma_f32 v[2:3], v[82:83], v[82:83], v[2:3]
	v_pk_fma_f32 v[74:75], v[130:131], v[106:107], v[160:161] neg_lo:[0,0,1] neg_hi:[0,0,1]
	v_pk_fma_f32 v[2:3], v[78:79], v[78:79], v[2:3]
	v_pk_fma_f32 v[70:71], v[130:131], v[126:127], v[160:161] neg_lo:[0,0,1] neg_hi:[0,0,1]
	v_pk_fma_f32 v[2:3], v[74:75], v[74:75], v[2:3]
	v_pk_fma_f32 v[66:67], v[130:131], v[122:123], v[160:161] neg_lo:[0,0,1] neg_hi:[0,0,1]
	v_pk_fma_f32 v[2:3], v[70:71], v[70:71], v[2:3]
	v_pk_fma_f32 v[30:31], v[130:131], v[118:119], v[160:161] neg_lo:[0,0,1] neg_hi:[0,0,1]
	v_pk_fma_f32 v[2:3], v[66:67], v[66:67], v[2:3]
	v_pk_fma_f32 v[26:27], v[130:131], v[114:115], v[160:161] neg_lo:[0,0,1] neg_hi:[0,0,1]
	v_pk_fma_f32 v[2:3], v[30:31], v[30:31], v[2:3]
	v_pk_fma_f32 v[22:23], v[130:131], v[110:111], v[160:161] neg_lo:[0,0,1] neg_hi:[0,0,1]
	v_pk_fma_f32 v[2:3], v[26:27], v[26:27], v[2:3]
	v_pk_fma_f32 v[18:19], v[130:131], v[46:47], v[160:161] neg_lo:[0,0,1] neg_hi:[0,0,1]
	v_pk_fma_f32 v[2:3], v[22:23], v[22:23], v[2:3]
	v_pk_fma_f32 v[10:11], v[158:159], v[38:39], v[160:161] op_sel:[0,0,1] op_sel_hi:[0,1,1] neg_lo:[0,0,1] neg_hi:[0,0,1]
	v_pk_mul_f32 v[162:163], v[62:63], v[62:63]
	v_pk_fma_f32 v[2:3], v[18:19], v[18:19], v[2:3]
	v_pk_fma_f32 v[14:15], v[130:131], v[42:43], v[160:161] neg_lo:[0,0,1] neg_hi:[0,0,1]
	v_pk_mul_f32 v[38:39], v[10:11], v[10:11]
	v_pk_fma_f32 v[42:43], v[14:15], v[14:15], v[2:3]
	v_pk_fma_f32 v[6:7], v[158:159], v[50:51], v[160:161] op_sel:[0,0,1] op_sel_hi:[0,1,1] neg_lo:[0,0,1] neg_hi:[0,0,1]
	v_pk_fma_f32 v[2:3], v[158:159], v[54:55], v[160:161] op_sel:[0,0,1] op_sel_hi:[0,1,1] neg_lo:[0,0,1] neg_hi:[0,0,1]
	v_mov_b32_e32 v55, v162
	v_mov_b32_e32 v162, v39
	v_pk_mul_f32 v[164:165], v[58:59], v[58:59]
	v_pk_mul_f32 v[46:47], v[6:7], v[6:7]
	v_mov_b32_e32 v54, v38
	v_pk_add_f32 v[38:39], v[162:163], v[42:43] op_sel:[0,1] op_sel_hi:[1,0]
	v_mov_b32_e32 v42, v47
	v_pk_add_f32 v[38:39], v[54:55], v[38:39]
	v_mov_b32_e32 v43, v165
	v_pk_mul_f32 v[166:167], v[34:35], v[34:35]
	v_pk_mul_f32 v[50:51], v[2:3], v[2:3]
	v_pk_add_f32 v[38:39], v[42:43], v[38:39]
	v_mov_b32_e32 v47, v164
	v_pk_add_f32 v[38:39], v[46:47], v[38:39]
	v_mov_b32_e32 v42, v51
	v_mov_b32_e32 v43, v167
	v_pk_add_f32 v[38:39], v[42:43], v[38:39]
	v_mov_b32_e32 v51, v166
	v_pk_add_f32 v[38:39], v[50:51], v[38:39]
	v_mov_b64_e32 v[46:47], s[0:1]
	v_mov_b32_e32 v50, v36
	v_mul_f32_e32 v36, v1, v216
	v_mov_b32_e32 v51, v56
	s_waitcnt lgkmcnt(0)
	s_nop 1
	v_add_f32_dpp v38, v38, v38 quad_perm:[1,0,3,2] row_mask:0xf bank_mask:0xf
	v_add_f32_dpp v39, v39, v39 quad_perm:[1,0,3,2] row_mask:0xf bank_mask:0xf
	v_mov_b32_e32 v102, v60
	v_mov_b32_e32 v103, v40
	v_mov_b32_e32 v56, v37
	v_mov_b32_e32 v40, v61
	s_waitcnt lgkmcnt(0)
; __device__ __forceinline__ float shx(float v, int lane, int mask) { return __int_as_float(__builtin_amdgcn_ds_bpermute((lane ^ mask) << 2, __float_as_int(v))); }
; __device__ __forceinline__ void retc_stream(const int wv, LAS unsigned char* lds, unsigned ldsb, const float* __restrict__ gn_g, const float* __restrict__ gn_b, const bf16_t* __restrict__ qkvr, const bf16_t* __restrict__ grb, const bf16_t* __restrict__ kv, ...
;     ...
;         for (int e = 0; e < 4; ++e) {
;             const int q = 16 * w + 4 * g + e;
;             const float xi = exp2f(lg2 * (float)(q - 127));
;             float sum = 0.f;
; #pragma unroll
;             for (int c = 0; c < 32; ++c) { acc[c][e] *= xi; sum += acc[c][e]; }
;             sum += shx(sum, lane, 1); sum += shx(sum, lane, 2); sum += shx(sum, lane, 4); sum += shx(sum, lane, 8);
;             const float mu = sum * (1.0f / 512.0f);
;             float var = 0.f;
; #pragma unroll
;             for (int c = 0; c < 32; ++c) { const float d = acc[c][e] - mu; var += d * d; }
;             var += shx(var, lane, 1); var += shx(var, lane, 2); var += shx(var, lane, 4); var += shx(var, lane, 8);
;             mu4[e] = mu; rs4[e] = rsqrtf(var * (1.0f / 512.0f) + EPS);
	s_nop 1
	v_add_f32_dpp v38, v38, v38 quad_perm:[2,3,0,1] row_mask:0xf bank_mask:0xf
	v_add_f32_dpp v39, v39, v39 quad_perm:[2,3,0,1] row_mask:0xf bank_mask:0xf
	s_waitcnt lgkmcnt(0)
	s_nop 1
	v_add_f32_dpp v38, v38, v38 row_half_mirror row_mask:0xf bank_mask:0xf
	v_add_f32_dpp v39, v39, v39 row_half_mirror row_mask:0xf bank_mask:0xf
	s_waitcnt lgkmcnt(0)
	s_nop 1
	v_add_f32_dpp v38, v38, v38 row_mirror row_mask:0xf bank_mask:0xf
	v_add_f32_dpp v39, v39, v39 row_mirror row_mask:0xf bank_mask:0xf
	s_nop 0
	v_pk_fma_f32 v[38:39], v[38:39], s[40:41], v[46:47] op_sel_hi:[1,0,0]
	s_nop 0
	v_mul_f32_e32 v42, 0x4b800000, v39
	v_cmp_gt_f32_e64 s[0:1], s36, v39
	v_cmp_gt_f32_e32 vcc, s36, v38
	s_nop 0
	v_cndmask_b32_e64 v39, v39, v42, s[0:1]
	v_rsq_f32_e32 v39, v39
	s_nop 0
	v_mul_f32_e32 v42, 0x45800000, v39
	v_cndmask_b32_e64 v110, v39, v42, s[0:1]
	v_mul_f32_e32 v39, 0x4b800000, v38
	v_cndmask_b32_e32 v38, v38, v39, vcc
	v_rsq_f32_e32 v38, v38
	v_mul_f32_e32 v30, v30, v110
	v_mul_f32_e32 v26, v26, v110
	v_mul_f32_e32 v22, v22, v110
	v_mul_f32_e32 v39, 0x45800000, v38
	v_cndmask_b32_e32 v111, v38, v39, vcc
	v_mul_f32_e32 v38, v1, v215
	v_cmp_gt_f32_e32 vcc, s41, v38
	v_mul_f32_e32 v18, v18, v110
	v_mul_f32_e32 v14, v14, v110
	v_cndmask_b32_e32 v38, 0, v187, vcc
	v_cndmask_b32_e32 v39, 0, v189, vcc
	v_cmp_gt_f32_e32 vcc, s41, v36
	v_fmac_f32_e32 v38, v1, v215
	v_exp_f32_e32 v38, v38
	v_cndmask_b32_e32 v36, 0, v187, vcc
	v_fmac_f32_e32 v36, v1, v216
	v_exp_f32_e32 v1, v36
	v_ldexp_f32 v98, v38, v39
	v_mov_b32_e32 v38, v64
	v_mov_b32_e32 v39, v52
	v_cndmask_b32_e32 v36, 0, v189, vcc
	v_pk_mul_f32 v[42:43], v[98:99], v[50:51] op_sel_hi:[0,1]
	v_pk_mul_f32 v[54:55], v[98:99], v[38:39] op_sel_hi:[0,1]
	v_pk_mul_f32 v[106:107], v[98:99], v[102:103] op_sel_hi:[0,1]
	v_ldexp_f32 v99, v1, v36
	v_mov_b32_e32 v114, v99
	v_mov_b32_e32 v52, v65
	v_pk_mul_f32 v[36:37], v[114:115], v[56:57] op_sel_hi:[0,1]
	v_pk_mul_f32 v[64:65], v[114:115], v[52:53] op_sel_hi:[0,1]
	v_pk_mul_f32 v[60:61], v[114:115], v[40:41] op_sel_hi:[0,1]
	v_mov_b32_e32 v118, v43
	v_mov_b32_e32 v119, v37
	v_mov_b32_e32 v43, v36
	v_mov_b32_e32 v36, v107
	v_mov_b32_e32 v37, v61
	v_mov_b32_e32 v107, v60
	v_mov_b32_e32 v60, v55
	v_mov_b32_e32 v61, v65
	v_mov_b32_e32 v55, v64
	v_pk_fma_f32 v[64:65], v[98:99], v[28:29], 0 op_sel_hi:[1,1,0]
	v_mul_f32_e32 v11, v11, v111
	v_pk_fma_f32 v[64:65], v[98:99], v[32:33], v[64:65]
	v_mul_f32_e32 v10, v10, v111
	v_pk_fma_f32 v[64:65], v[98:99], v[24:25], v[64:65]
	v_mul_f32_e32 v7, v7, v111
	v_pk_fma_f32 v[64:65], v[98:99], v[20:21], v[64:65]
	v_mul_f32_e32 v6, v6, v111
	v_pk_fma_f32 v[64:65], v[98:99], v[16:17], v[64:65]
	v_mul_f32_e32 v3, v3, v111
	v_pk_fma_f32 v[64:65], v[98:99], v[12:13], v[64:65]
	v_mul_f32_e32 v2, v2, v111
	v_pk_fma_f32 v[64:65], v[98:99], v[8:9], v[64:65]
	s_nop 0
	v_pk_fma_f32 v[64:65], v[98:99], v[4:5], v[64:65]
	s_nop 0
	v_pk_fma_f32 v[64:65], v[98:99], v[96:97], v[64:65]
	s_nop 0
	v_pk_fma_f32 v[64:65], v[98:99], v[92:93], v[64:65]
	s_nop 0
	v_pk_fma_f32 v[64:65], v[98:99], v[88:89], v[64:65]
	s_nop 0
	v_pk_fma_f32 v[64:65], v[98:99], v[84:85], v[64:65]
	s_nop 0
	v_pk_fma_f32 v[64:65], v[98:99], v[80:81], v[64:65]
	s_nop 0
	v_pk_fma_f32 v[64:65], v[98:99], v[76:77], v[64:65]
	s_nop 0
	v_pk_fma_f32 v[64:65], v[98:99], v[72:73], v[64:65]
	s_nop 0
	v_pk_fma_f32 v[64:65], v[98:99], v[68:69], v[64:65]
	s_nop 0
	v_pk_fma_f32 v[64:65], v[98:99], v[104:105], v[64:65]
	s_nop 0
	v_pk_fma_f32 v[64:65], v[98:99], v[100:101], v[64:65]
	s_nop 0
	v_pk_fma_f32 v[64:65], v[98:99], v[108:109], v[64:65]
	s_nop 0
	v_pk_fma_f32 v[64:65], v[98:99], v[128:129], v[64:65]
	s_nop 0
	v_pk_fma_f32 v[64:65], v[98:99], v[124:125], v[64:65]
	s_nop 0
	v_pk_fma_f32 v[64:65], v[98:99], v[120:121], v[64:65]
	s_nop 0
	v_pk_fma_f32 v[64:65], v[98:99], v[116:117], v[64:65]
	s_nop 0
	v_pk_fma_f32 v[64:65], v[98:99], v[112:113], v[64:65]
	s_nop 0
	v_pk_fma_f32 v[64:65], v[98:99], v[48:49], v[64:65]
	s_nop 0
	v_pk_fma_f32 v[64:65], v[98:99], v[44:45], v[64:65]
	s_nop 0
	v_pk_add_f32 v[36:37], v[64:65], v[36:37]
	s_nop 0
	v_pk_add_f32 v[36:37], v[36:37], v[106:107]
	s_nop 0
	v_pk_add_f32 v[36:37], v[36:37], v[60:61]
	s_nop 0
	v_pk_add_f32 v[36:37], v[36:37], v[54:55]
	s_nop 0
	v_pk_add_f32 v[36:37], v[36:37], v[118:119]
	s_nop 0
	v_pk_add_f32 v[36:37], v[36:37], v[42:43]
	s_waitcnt lgkmcnt(0)
	s_nop 1
	v_add_f32_dpp v36, v36, v36 quad_perm:[1,0,3,2] row_mask:0xf bank_mask:0xf
	v_add_f32_dpp v37, v37, v37 quad_perm:[1,0,3,2] row_mask:0xf bank_mask:0xf
	s_waitcnt lgkmcnt(0)
	s_nop 1
	v_add_f32_dpp v36, v36, v36 quad_perm:[2,3,0,1] row_mask:0xf bank_mask:0xf
	v_add_f32_dpp v37, v37, v37 quad_perm:[2,3,0,1] row_mask:0xf bank_mask:0xf
	s_waitcnt lgkmcnt(0)
	s_nop 1
	v_add_f32_dpp v36, v36, v36 row_half_mirror row_mask:0xf bank_mask:0xf
	v_add_f32_dpp v37, v37, v37 row_half_mirror row_mask:0xf bank_mask:0xf
	s_waitcnt lgkmcnt(0)
; __device__ __forceinline__ float shx(float v, int lane, int mask) { return __int_as_float(__builtin_amdgcn_ds_bpermute((lane ^ mask) << 2, __float_as_int(v))); }
; __device__ __forceinline__ void retc_stream(const int wv, LAS unsigned char* lds, unsigned ldsb, const float* __restrict__ gn_g, const float* __restrict__ gn_b, const bf16_t* __restrict__ qkvr, const bf16_t* __restrict__ grb, const bf16_t* __restrict__ kv, ...
;     ...
;             for (int c = 0; c < 32; ++c) { acc[c][e] *= xi; sum += acc[c][e]; }
;             sum += shx(sum, lane, 1); sum += shx(sum, lane, 2); sum += shx(sum, lane, 4); sum += shx(sum, lane, 8);
;             const float mu = sum * (1.0f / 512.0f);
;             float var = 0.f;
; #pragma unroll
;             for (int c = 0; c < 32; ++c) { const float d = acc[c][e] - mu; var += d * d; }
;             var += shx(var, lane, 1); var += shx(var, lane, 2); var += shx(var, lane, 4); var += shx(var, lane, 8);
;             mu4[e] = mu; rs4[e] = rsqrtf(var * (1.0f / 512.0f) + EPS);
	s_nop 1
	v_add_f32_dpp v36, v36, v36 row_mirror row_mask:0xf bank_mask:0xf
	v_add_f32_dpp v37, v37, v37 row_mirror row_mask:0xf bank_mask:0xf
	s_nop 0
	v_pk_mul_f32 v[118:119], v[36:37], s[40:41] op_sel_hi:[1,0]
	s_nop 0
	v_pk_fma_f32 v[160:161], v[98:99], v[32:33], v[118:119] neg_lo:[0,0,1] neg_hi:[0,0,1]
	v_pk_fma_f32 v[158:159], v[98:99], v[28:29], v[118:119] neg_lo:[0,0,1] neg_hi:[0,0,1]
	v_pk_mul_f32 v[28:29], v[160:161], v[160:161]
	v_pk_fma_f32 v[162:163], v[98:99], v[24:25], v[118:119] neg_lo:[0,0,1] neg_hi:[0,0,1]
	v_pk_fma_f32 v[28:29], v[158:159], v[158:159], v[28:29]
	v_pk_fma_f32 v[164:165], v[98:99], v[20:21], v[118:119] neg_lo:[0,0,1] neg_hi:[0,0,1]
	v_pk_fma_f32 v[24:25], v[162:163], v[162:163], v[28:29]
	v_pk_fma_f32 v[166:167], v[98:99], v[16:17], v[118:119] neg_lo:[0,0,1] neg_hi:[0,0,1]
	v_pk_fma_f32 v[20:21], v[164:165], v[164:165], v[24:25]
	v_pk_fma_f32 v[168:169], v[98:99], v[12:13], v[118:119] neg_lo:[0,0,1] neg_hi:[0,0,1]
	v_pk_fma_f32 v[16:17], v[166:167], v[166:167], v[20:21]
	v_pk_fma_f32 v[170:171], v[98:99], v[8:9], v[118:119] neg_lo:[0,0,1] neg_hi:[0,0,1]
	v_pk_fma_f32 v[12:13], v[168:169], v[168:169], v[16:17]
	v_pk_fma_f32 v[106:107], v[98:99], v[4:5], v[118:119] neg_lo:[0,0,1] neg_hi:[0,0,1]
	v_pk_fma_f32 v[8:9], v[170:171], v[170:171], v[12:13]
	v_pk_fma_f32 v[42:43], v[98:99], v[102:103], v[118:119] op_sel_hi:[0,1,0] neg_lo:[0,0,1] neg_hi:[0,0,1]
	v_pk_fma_f32 v[4:5], v[106:107], v[106:107], v[8:9]
	v_pk_fma_f32 v[102:103], v[98:99], v[96:97], v[118:119] neg_lo:[0,0,1] neg_hi:[0,0,1]
	v_pk_fma_f32 v[96:97], v[98:99], v[92:93], v[118:119] neg_lo:[0,0,1] neg_hi:[0,0,1]
	v_pk_fma_f32 v[4:5], v[102:103], v[102:103], v[4:5]
	v_pk_fma_f32 v[92:93], v[98:99], v[88:89], v[118:119] neg_lo:[0,0,1] neg_hi:[0,0,1]
	v_pk_fma_f32 v[4:5], v[96:97], v[96:97], v[4:5]
	v_pk_fma_f32 v[88:89], v[98:99], v[84:85], v[118:119] neg_lo:[0,0,1] neg_hi:[0,0,1]
	v_pk_fma_f32 v[4:5], v[92:93], v[92:93], v[4:5]
	v_pk_fma_f32 v[84:85], v[98:99], v[80:81], v[118:119] neg_lo:[0,0,1] neg_hi:[0,0,1]
	v_pk_fma_f32 v[4:5], v[88:89], v[88:89], v[4:5]
	v_pk_fma_f32 v[80:81], v[98:99], v[76:77], v[118:119] neg_lo:[0,0,1] neg_hi:[0,0,1]
	v_pk_fma_f32 v[4:5], v[84:85], v[84:85], v[4:5]
	v_pk_fma_f32 v[76:77], v[98:99], v[72:73], v[118:119] neg_lo:[0,0,1] neg_hi:[0,0,1]
	v_pk_fma_f32 v[4:5], v[80:81], v[80:81], v[4:5]
	v_pk_fma_f32 v[72:73], v[98:99], v[68:69], v[118:119] neg_lo:[0,0,1] neg_hi:[0,0,1]
	v_pk_fma_f32 v[4:5], v[76:77], v[76:77], v[4:5]
	v_pk_fma_f32 v[68:69], v[98:99], v[104:105], v[118:119] neg_lo:[0,0,1] neg_hi:[0,0,1]
	v_pk_fma_f32 v[4:5], v[72:73], v[72:73], v[4:5]
	v_pk_fma_f32 v[64:65], v[98:99], v[100:101], v[118:119] neg_lo:[0,0,1] neg_hi:[0,0,1]
	v_pk_fma_f32 v[4:5], v[68:69], v[68:69], v[4:5]
	v_pk_fma_f32 v[60:61], v[98:99], v[108:109], v[118:119] neg_lo:[0,0,1] neg_hi:[0,0,1]
	v_pk_fma_f32 v[4:5], v[64:65], v[64:65], v[4:5]
	v_pk_fma_f32 v[54:55], v[98:99], v[128:129], v[118:119] neg_lo:[0,0,1] neg_hi:[0,0,1]
	v_pk_fma_f32 v[4:5], v[60:61], v[60:61], v[4:5]
	v_pk_fma_f32 v[36:37], v[98:99], v[50:51], v[118:119] op_sel_hi:[0,1,0] neg_lo:[0,0,1] neg_hi:[0,0,1]
	v_pk_fma_f32 v[4:5], v[54:55], v[54:55], v[4:5]
	v_pk_fma_f32 v[50:51], v[98:99], v[124:125], v[118:119] neg_lo:[0,0,1] neg_hi:[0,0,1]
	v_pk_fma_f32 v[32:33], v[98:99], v[120:121], v[118:119] neg_lo:[0,0,1] neg_hi:[0,0,1]
	v_pk_fma_f32 v[4:5], v[50:51], v[50:51], v[4:5]
	v_pk_fma_f32 v[28:29], v[98:99], v[116:117], v[118:119] neg_lo:[0,0,1] neg_hi:[0,0,1]
	v_pk_fma_f32 v[4:5], v[32:33], v[32:33], v[4:5]
	v_pk_fma_f32 v[24:25], v[98:99], v[112:113], v[118:119] neg_lo:[0,0,1] neg_hi:[0,0,1]
	v_pk_fma_f32 v[4:5], v[28:29], v[28:29], v[4:5]
	v_pk_fma_f32 v[20:21], v[98:99], v[48:49], v[118:119] neg_lo:[0,0,1] neg_hi:[0,0,1]
	v_pk_fma_f32 v[4:5], v[24:25], v[24:25], v[4:5]
	v_pk_fma_f32 v[12:13], v[114:115], v[40:41], v[118:119] op_sel:[0,0,1] op_sel_hi:[0,1,1] neg_lo:[0,0,1] neg_hi:[0,0,1]
	v_pk_mul_f32 v[122:123], v[42:43], v[42:43]
	v_pk_fma_f32 v[4:5], v[20:21], v[20:21], v[4:5]
	v_pk_fma_f32 v[16:17], v[98:99], v[44:45], v[118:119] neg_lo:[0,0,1] neg_hi:[0,0,1]
	v_pk_mul_f32 v[40:41], v[12:13], v[12:13]
	v_pk_fma_f32 v[38:39], v[98:99], v[38:39], v[118:119] op_sel_hi:[0,1,0] neg_lo:[0,0,1] neg_hi:[0,0,1]
	v_pk_fma_f32 v[44:45], v[16:17], v[16:17], v[4:5]
	v_pk_fma_f32 v[8:9], v[114:115], v[52:53], v[118:119] op_sel:[0,0,1] op_sel_hi:[0,1,1] neg_lo:[0,0,1] neg_hi:[0,0,1]
	v_pk_fma_f32 v[4:5], v[114:115], v[56:57], v[118:119] op_sel:[0,0,1] op_sel_hi:[0,1,1] neg_lo:[0,0,1] neg_hi:[0,0,1]
	v_mov_b32_e32 v57, v122
	v_mov_b32_e32 v122, v41
	v_pk_mul_f32 v[126:127], v[38:39], v[38:39]
	v_pk_mul_f32 v[48:49], v[8:9], v[8:9]
	v_mov_b32_e32 v56, v40
	v_pk_add_f32 v[40:41], v[122:123], v[44:45] op_sel:[0,1] op_sel_hi:[1,0]
	v_mov_b32_e32 v44, v49
	v_pk_add_f32 v[40:41], v[56:57], v[40:41]
	v_mov_b32_e32 v45, v127
	v_pk_mul_f32 v[130:131], v[36:37], v[36:37]
	v_pk_mul_f32 v[52:53], v[4:5], v[4:5]
	v_pk_add_f32 v[40:41], v[44:45], v[40:41]
	v_mov_b32_e32 v49, v126
	v_pk_add_f32 v[40:41], v[48:49], v[40:41]
	v_mov_b32_e32 v44, v53
	v_mov_b32_e32 v45, v131
	v_pk_add_f32 v[40:41], v[44:45], v[40:41]
	v_mov_b32_e32 v53, v130
	v_pk_add_f32 v[40:41], v[52:53], v[40:41]
	s_waitcnt lgkmcnt(0)
	s_nop 1
	v_add_f32_dpp v40, v40, v40 quad_perm:[1,0,3,2] row_mask:0xf bank_mask:0xf
	v_add_f32_dpp v41, v41, v41 quad_perm:[1,0,3,2] row_mask:0xf bank_mask:0xf
	s_waitcnt lgkmcnt(0)
	s_nop 1
	v_add_f32_dpp v40, v40, v40 quad_perm:[2,3,0,1] row_mask:0xf bank_mask:0xf
	v_add_f32_dpp v41, v41, v41 quad_perm:[2,3,0,1] row_mask:0xf bank_mask:0xf
	s_waitcnt lgkmcnt(0)
; #define LAS __attribute__((address_space(3)))
; __device__ __forceinline__ float shx(float v, int lane, int mask) { return __int_as_float(__builtin_amdgcn_ds_bpermute((lane ^ mask) << 2, __float_as_int(v))); }
; __device__ __forceinline__ bf16_t f2bf(float f) { return (bf16_t)(cvt_pk_bf16(f, 0.f) & 0xffffu); }
; #define LBAR() do { asm volatile("s_waitcnt lgkmcnt(0)" ::: "memory"); __builtin_amdgcn_s_barrier(); asm volatile("" ::: "memory"); } while (0)
; __device__ __forceinline__ void retc_stream(const int wv, LAS unsigned char* lds, unsigned ldsb, const float* __restrict__ gn_g, const float* __restrict__ gn_b, const bf16_t* __restrict__ qkvr, const bf16_t* __restrict__ grb, const bf16_t* __restrict__ kv, ...
;     ...
;             var += shx(var, lane, 1); var += shx(var, lane, 2); var += shx(var, lane, 4); var += shx(var, lane, 8);
;             mu4[e] = mu; rs4[e] = rsqrtf(var * (1.0f / 512.0f) + EPS);
;         }
;         LBAR();
;         {
;             unsigned wb = (unsigned)(16 * w + 4 * g) * 1024u + (unsigned)li * 2u; asm volatile("" : "+v"(wb));
; #pragma unroll
;             for (int c = 0; c < 32; ++c) {
;                 const unsigned co = (unsigned)(((2 * c) ^ (2 * g)) * 16);
; #pragma unroll
;                 for (int e = 0; e < 4; ++e)
;                     *(LAS bf16_t*)(lds + wb + e * 1024 + co) = f2bf((acc[c][e] - mu4[e]) * rs4[e]);
;             }
	s_nop 1
	v_add_f32_dpp v40, v40, v40 row_half_mirror row_mask:0xf bank_mask:0xf
	v_add_f32_dpp v41, v41, v41 row_half_mirror row_mask:0xf bank_mask:0xf
	s_waitcnt lgkmcnt(0)
	s_nop 1
	v_add_f32_dpp v40, v40, v40 row_mirror row_mask:0xf bank_mask:0xf
	v_add_f32_dpp v41, v41, v41 row_mirror row_mask:0xf bank_mask:0xf
	s_nop 0
	v_pk_fma_f32 v[40:41], v[40:41], s[40:41], v[46:47] op_sel_hi:[1,0,0]
	v_mul_f32_e32 v45, v156, v110
	v_mul_f32_e32 v1, 0x4b800000, v41
	v_cmp_gt_f32_e64 s[0:1], s36, v41
	v_cmp_gt_f32_e32 vcc, s36, v40
	v_mul_f32_e32 v46, v154, v110
	v_cndmask_b32_e64 v1, v41, v1, s[0:1]
	v_rsq_f32_e32 v1, v1
	v_mul_f32_e32 v47, v152, v110
	v_mul_f32_e32 v41, 0x45800000, v1
	v_cndmask_b32_e64 v1, v1, v41, s[0:1]
	v_mul_f32_e32 v41, 0x4b800000, v40
	v_cndmask_b32_e32 v40, v40, v41, vcc
	v_rsq_f32_e32 v40, v40
	s_add_u32 s0, s18, s12
	s_addc_u32 s1, s19, s13
	v_mul_f32_e32 v41, 0x45800000, v40
	v_cndmask_b32_e32 v40, v40, v41, vcc
	v_mov_b32_e32 v41, v212
	v_cvt_pk_bf16_f32 v45, v45, v0
	s_nop 0
	v_add_u32_e32 v41, 0, v41
	v_add_u32_e32 v44, v41, v217
	ds_write_b16 v44, v45
	v_mul_f32_e32 v45, v157, v111
	v_cvt_pk_bf16_f32 v45, v45, v0
	ds_write_b16 v44, v45 offset:1024
	v_mul_f32_e32 v45, v158, v1
	v_cvt_pk_bf16_f32 v45, v45, v0
	ds_write_b16 v44, v45 offset:2048
	v_mul_f32_e32 v45, v159, v40
	v_cvt_pk_bf16_f32 v45, v45, v0
	ds_write_b16 v44, v45 offset:3072
	v_add_u32_e32 v45, v41, v218
	v_cvt_pk_bf16_f32 v46, v46, v0
	ds_write_b16 v45, v46
	v_mul_f32_e32 v46, v155, v111
	v_cvt_pk_bf16_f32 v46, v46, v0
	ds_write_b16 v45, v46 offset:1024
	v_mul_f32_e32 v46, v160, v1
	v_cvt_pk_bf16_f32 v46, v46, v0
	ds_write_b16 v45, v46 offset:2048
	v_mul_f32_e32 v46, v161, v40
	v_cvt_pk_bf16_f32 v46, v46, v0
	ds_write_b16 v45, v46 offset:3072
	v_add_u32_e32 v46, v41, v219
	v_cvt_pk_bf16_f32 v47, v47, v0
	ds_write_b16 v46, v47
	v_mul_f32_e32 v47, v153, v111
	v_cvt_pk_bf16_f32 v47, v47, v0
	ds_write_b16 v46, v47 offset:1024
	v_mul_f32_e32 v47, v162, v1
	v_cvt_pk_bf16_f32 v47, v47, v0
	ds_write_b16 v46, v47 offset:2048
	v_mul_f32_e32 v47, v163, v40
	v_cvt_pk_bf16_f32 v47, v47, v0
	ds_write_b16 v46, v47 offset:3072
	v_mul_f32_e32 v47, v150, v110
	v_add_u32_e32 v41, v41, v220
	v_cvt_pk_bf16_f32 v47, v47, v0
	ds_write_b16 v41, v47
	v_mul_f32_e32 v47, v151, v111
	v_cvt_pk_bf16_f32 v47, v47, v0
	ds_write_b16 v41, v47 offset:1024
	v_mul_f32_e32 v47, v164, v1
	v_cvt_pk_bf16_f32 v47, v47, v0
	ds_write_b16 v41, v47 offset:2048
	v_mul_f32_e32 v47, v165, v40
	v_cvt_pk_bf16_f32 v47, v47, v0
	ds_write_b16 v41, v47 offset:3072
	v_mul_f32_e32 v47, v148, v110
	v_cvt_pk_bf16_f32 v47, v47, v0
	ds_write_b16 v44, v47 offset:128
	v_mul_f32_e32 v47, v149, v111
	v_cvt_pk_bf16_f32 v47, v47, v0
	ds_write_b16 v44, v47 offset:1152
	v_mul_f32_e32 v47, v166, v1
	v_cvt_pk_bf16_f32 v47, v47, v0
	ds_write_b16 v44, v47 offset:2176
	v_mul_f32_e32 v47, v167, v40
	v_cvt_pk_bf16_f32 v47, v47, v0
	ds_write_b16 v44, v47 offset:3200
	v_mul_f32_e32 v47, v146, v110
	v_cvt_pk_bf16_f32 v47, v47, v0
	ds_write_b16 v45, v47 offset:128
	v_mul_f32_e32 v47, v147, v111
	v_cvt_pk_bf16_f32 v47, v47, v0
	ds_write_b16 v45, v47 offset:1152
	v_mul_f32_e32 v47, v168, v1
	v_cvt_pk_bf16_f32 v47, v47, v0
	ds_write_b16 v45, v47 offset:2176
	v_mul_f32_e32 v47, v169, v40
	v_cvt_pk_bf16_f32 v47, v47, v0
	ds_write_b16 v45, v47 offset:3200
	v_mul_f32_e32 v47, v144, v110
	v_cvt_pk_bf16_f32 v47, v47, v0
	ds_write_b16 v46, v47 offset:128
	v_mul_f32_e32 v47, v145, v111
	v_cvt_pk_bf16_f32 v47, v47, v0
	ds_write_b16 v46, v47 offset:1152
	v_mul_f32_e32 v47, v170, v1
	v_cvt_pk_bf16_f32 v47, v47, v0
	ds_write_b16 v46, v47 offset:2176
	v_mul_f32_e32 v47, v171, v40
	v_cvt_pk_bf16_f32 v47, v47, v0
	ds_write_b16 v46, v47 offset:3200
	v_mul_f32_e32 v47, v142, v110
	v_cvt_pk_bf16_f32 v47, v47, v0
	ds_write_b16 v41, v47 offset:128
	v_mul_f32_e32 v47, v143, v111
	v_cvt_pk_bf16_f32 v47, v47, v0
	ds_write_b16 v41, v47 offset:1152
	v_mul_f32_e32 v47, v106, v1
	v_cvt_pk_bf16_f32 v47, v47, v0
	ds_write_b16 v41, v47 offset:2176
	v_mul_f32_e32 v47, v107, v40
	v_cvt_pk_bf16_f32 v47, v47, v0
	ds_write_b16 v41, v47 offset:3200
	v_mul_f32_e32 v47, v140, v110
	v_cvt_pk_bf16_f32 v47, v47, v0
	ds_write_b16 v44, v47 offset:256
	v_mul_f32_e32 v47, v141, v111
	v_cvt_pk_bf16_f32 v47, v47, v0
	ds_write_b16 v44, v47 offset:1280
	v_mul_f32_e32 v47, v102, v1
	v_cvt_pk_bf16_f32 v47, v47, v0
	ds_write_b16 v44, v47 offset:2304
	v_mul_f32_e32 v47, v103, v40
	v_cvt_pk_bf16_f32 v47, v47, v0
	ds_write_b16 v44, v47 offset:3328
	v_mul_f32_e32 v47, v138, v110
	v_cvt_pk_bf16_f32 v47, v47, v0
	ds_write_b16 v45, v47 offset:256
	v_mul_f32_e32 v47, v139, v111
	v_cvt_pk_bf16_f32 v47, v47, v0
	ds_write_b16 v45, v47 offset:1280
	v_mul_f32_e32 v47, v96, v1
	v_cvt_pk_bf16_f32 v47, v47, v0
	ds_write_b16 v45, v47 offset:2304
	v_mul_f32_e32 v47, v97, v40
	v_cvt_pk_bf16_f32 v47, v47, v0
	ds_write_b16 v45, v47 offset:3328
	v_mul_f32_e32 v47, v136, v110
	v_cvt_pk_bf16_f32 v47, v47, v0
	ds_write_b16 v46, v47 offset:256
	v_mul_f32_e32 v47, v137, v111
	v_cvt_pk_bf16_f32 v47, v47, v0
	ds_write_b16 v46, v47 offset:1280
	v_mul_f32_e32 v47, v92, v1
	v_cvt_pk_bf16_f32 v47, v47, v0
	ds_write_b16 v46, v47 offset:2304
	v_mul_f32_e32 v47, v93, v40
	v_cvt_pk_bf16_f32 v47, v47, v0
	ds_write_b16 v46, v47 offset:3328
	v_mul_f32_e32 v47, v134, v110
	v_cvt_pk_bf16_f32 v47, v47, v0
	ds_write_b16 v41, v47 offset:256
	v_mul_f32_e32 v47, v135, v111
	v_cvt_pk_bf16_f32 v47, v47, v0
	ds_write_b16 v41, v47 offset:1280
	v_mul_f32_e32 v47, v88, v1
	v_cvt_pk_bf16_f32 v47, v47, v0
	ds_write_b16 v41, v47 offset:2304
	v_mul_f32_e32 v47, v89, v40
	v_cvt_pk_bf16_f32 v47, v47, v0
	ds_write_b16 v41, v47 offset:3328
; #define LAS __attribute__((address_space(3)))
; __device__ __forceinline__ bf16_t f2bf(float f) { return (bf16_t)(cvt_pk_bf16(f, 0.f) & 0xffffu); }
; __device__ __forceinline__ void retc_stream(const int wv, LAS unsigned char* lds, unsigned ldsb, const float* __restrict__ gn_g, const float* __restrict__ gn_b, const bf16_t* __restrict__ qkvr, const bf16_t* __restrict__ grb, const bf16_t* __restrict__ kv, ...
;     ...
;             unsigned wb = (unsigned)(16 * w + 4 * g) * 1024u + (unsigned)li * 2u; asm volatile("" : "+v"(wb));
; #pragma unroll
;             for (int c = 0; c < 32; ++c) {
;                 const unsigned co = (unsigned)(((2 * c) ^ (2 * g)) * 16);
; #pragma unroll
;                 for (int e = 0; e < 4; ++e)
;                     *(LAS bf16_t*)(lds + wb + e * 1024 + co) = f2bf((acc[c][e] - mu4[e]) * rs4[e]);
;             }
	v_mul_f32_e32 v47, v132, v110
	v_cvt_pk_bf16_f32 v47, v47, v0
	ds_write_b16 v44, v47 offset:384
	v_mul_f32_e32 v47, v133, v111
	v_cvt_pk_bf16_f32 v47, v47, v0
	ds_write_b16 v44, v47 offset:1408
	v_mul_f32_e32 v47, v84, v1
	v_cvt_pk_bf16_f32 v47, v47, v0
	ds_write_b16 v44, v47 offset:2432
	v_mul_f32_e32 v47, v85, v40
	v_cvt_pk_bf16_f32 v47, v47, v0
	ds_write_b16 v44, v47 offset:3456
	v_mul_f32_e32 v47, v94, v110
	v_cvt_pk_bf16_f32 v47, v47, v0
	ds_write_b16 v45, v47 offset:384
	v_mul_f32_e32 v47, v95, v111
	v_cvt_pk_bf16_f32 v47, v47, v0
	ds_write_b16 v45, v47 offset:1408
	v_mul_f32_e32 v47, v80, v1
	v_cvt_pk_bf16_f32 v47, v47, v0
	ds_write_b16 v45, v47 offset:2432
	v_mul_f32_e32 v47, v81, v40
	v_cvt_pk_bf16_f32 v47, v47, v0
	ds_write_b16 v45, v47 offset:3456
	v_mul_f32_e32 v47, v90, v110
	v_cvt_pk_bf16_f32 v47, v47, v0
	ds_write_b16 v46, v47 offset:384
	v_mul_f32_e32 v47, v91, v111
	v_cvt_pk_bf16_f32 v47, v47, v0
	ds_write_b16 v46, v47 offset:1408
	v_mul_f32_e32 v47, v76, v1
	v_cvt_pk_bf16_f32 v47, v47, v0
	ds_write_b16 v46, v47 offset:2432
	v_mul_f32_e32 v47, v77, v40
	v_cvt_pk_bf16_f32 v47, v47, v0
	ds_write_b16 v46, v47 offset:3456
	v_mul_f32_e32 v47, v86, v110
	v_cvt_pk_bf16_f32 v47, v47, v0
	ds_write_b16 v41, v47 offset:384
	v_mul_f32_e32 v47, v87, v111
	v_cvt_pk_bf16_f32 v47, v47, v0
	ds_write_b16 v41, v47 offset:1408
	v_mul_f32_e32 v47, v72, v1
	v_cvt_pk_bf16_f32 v47, v47, v0
	ds_write_b16 v41, v47 offset:2432
	v_mul_f32_e32 v47, v73, v40
	v_cvt_pk_bf16_f32 v47, v47, v0
	ds_write_b16 v41, v47 offset:3456
	v_mul_f32_e32 v47, v82, v110
	v_cvt_pk_bf16_f32 v47, v47, v0
	ds_write_b16 v44, v47 offset:512
	v_mul_f32_e32 v47, v83, v111
	v_cvt_pk_bf16_f32 v47, v47, v0
	ds_write_b16 v44, v47 offset:1536
	v_mul_f32_e32 v47, v68, v1
	v_cvt_pk_bf16_f32 v47, v47, v0
	ds_write_b16 v44, v47 offset:2560
	v_mul_f32_e32 v47, v69, v40
	v_cvt_pk_bf16_f32 v47, v47, v0
	ds_write_b16 v44, v47 offset:3584
	v_mul_f32_e32 v47, v78, v110
	v_cvt_pk_bf16_f32 v47, v47, v0
	ds_write_b16 v45, v47 offset:512
	v_mul_f32_e32 v47, v79, v111
	v_cvt_pk_bf16_f32 v47, v47, v0
	ds_write_b16 v45, v47 offset:1536
	v_mul_f32_e32 v47, v64, v1
	v_cvt_pk_bf16_f32 v47, v47, v0
	ds_write_b16 v45, v47 offset:2560
	v_mul_f32_e32 v47, v65, v40
	v_cvt_pk_bf16_f32 v47, v47, v0
	ds_write_b16 v45, v47 offset:3584
	v_mul_f32_e32 v47, v74, v110
	v_cvt_pk_bf16_f32 v47, v47, v0
	ds_write_b16 v46, v47 offset:512
	v_mul_f32_e32 v47, v75, v111
	v_cvt_pk_bf16_f32 v47, v47, v0
	ds_write_b16 v46, v47 offset:1536
	v_mul_f32_e32 v47, v60, v1
	v_cvt_pk_bf16_f32 v47, v47, v0
	ds_write_b16 v46, v47 offset:2560
	v_mul_f32_e32 v47, v61, v40
	v_cvt_pk_bf16_f32 v47, v47, v0
	ds_write_b16 v46, v47 offset:3584
	v_mul_f32_e32 v47, v70, v110
	v_cvt_pk_bf16_f32 v47, v47, v0
	ds_write_b16 v41, v47 offset:512
	v_mul_f32_e32 v47, v71, v111
	v_cvt_pk_bf16_f32 v47, v47, v0
	ds_write_b16 v41, v47 offset:1536
	v_mul_f32_e32 v47, v54, v1
	v_cvt_pk_bf16_f32 v47, v47, v0
	ds_write_b16 v41, v47 offset:2560
	v_mul_f32_e32 v47, v55, v40
	v_cvt_pk_bf16_f32 v47, v47, v0
	ds_write_b16 v41, v47 offset:3584
	v_mul_f32_e32 v47, v66, v110
	v_cvt_pk_bf16_f32 v47, v47, v0
	ds_write_b16 v44, v47 offset:640
	v_mul_f32_e32 v47, v67, v111
	v_cvt_pk_bf16_f32 v47, v47, v0
	ds_write_b16 v44, v47 offset:1664
	v_mul_f32_e32 v47, v50, v1
	v_cvt_pk_bf16_f32 v47, v47, v0
	ds_write_b16 v44, v47 offset:2688
	v_mul_f32_e32 v47, v51, v40
	v_cvt_pk_bf16_f32 v47, v47, v0
	ds_write_b16 v44, v47 offset:3712
	v_cvt_pk_bf16_f32 v30, v30, v0
	ds_write_b16 v45, v30 offset:640
	v_mul_f32_e32 v30, v31, v111
	v_cvt_pk_bf16_f32 v30, v30, v0
	ds_write_b16 v45, v30 offset:1664
	v_mul_f32_e32 v30, v32, v1
	v_cvt_pk_bf16_f32 v30, v30, v0
	ds_write_b16 v45, v30 offset:2688
	v_mul_f32_e32 v30, v33, v40
	v_cvt_pk_bf16_f32 v30, v30, v0
	ds_write_b16 v45, v30 offset:3712
	v_cvt_pk_bf16_f32 v26, v26, v0
	ds_write_b16 v46, v26 offset:640
	v_mul_f32_e32 v26, v27, v111
	v_cvt_pk_bf16_f32 v26, v26, v0
	ds_write_b16 v46, v26 offset:1664
	v_mul_f32_e32 v26, v28, v1
	v_cvt_pk_bf16_f32 v26, v26, v0
	ds_write_b16 v46, v26 offset:2688
	v_mul_f32_e32 v26, v29, v40
	v_cvt_pk_bf16_f32 v26, v26, v0
	ds_write_b16 v46, v26 offset:3712
	v_cvt_pk_bf16_f32 v22, v22, v0
	ds_write_b16 v41, v22 offset:640
	v_mul_f32_e32 v22, v23, v111
	v_cvt_pk_bf16_f32 v22, v22, v0
	ds_write_b16 v41, v22 offset:1664
	v_mul_f32_e32 v22, v24, v1
	v_cvt_pk_bf16_f32 v22, v22, v0
	ds_write_b16 v41, v22 offset:2688
	v_mul_f32_e32 v22, v25, v40
	v_cvt_pk_bf16_f32 v22, v22, v0
	ds_write_b16 v41, v22 offset:3712
	v_cvt_pk_bf16_f32 v18, v18, v0
	ds_write_b16 v44, v18 offset:768
	v_mul_f32_e32 v18, v19, v111
	v_cvt_pk_bf16_f32 v18, v18, v0
	ds_write_b16 v44, v18 offset:1792
	v_mul_f32_e32 v18, v20, v1
	v_cvt_pk_bf16_f32 v18, v18, v0
	ds_write_b16 v44, v18 offset:2816
	v_mul_f32_e32 v18, v21, v40
	v_cvt_pk_bf16_f32 v18, v18, v0
	ds_write_b16 v44, v18 offset:3840
	v_cvt_pk_bf16_f32 v14, v14, v0
	ds_write_b16 v45, v14 offset:768
	v_mul_f32_e32 v14, v15, v111
	v_cvt_pk_bf16_f32 v14, v14, v0
	ds_write_b16 v45, v14 offset:1792
	v_mul_f32_e32 v14, v16, v1
	v_cvt_pk_bf16_f32 v14, v14, v0
	ds_write_b16 v45, v14 offset:2816
	v_mul_f32_e32 v14, v17, v40
	v_cvt_pk_bf16_f32 v14, v14, v0
	ds_write_b16 v45, v14 offset:3840
	v_mul_f32_e32 v14, v63, v110
	v_cvt_pk_bf16_f32 v14, v14, v0
	ds_write_b16 v46, v14 offset:768
	v_cvt_pk_bf16_f32 v11, v11, v0
	ds_write_b16 v46, v11 offset:1792
	v_mul_f32_e32 v11, v43, v1
	v_cvt_pk_bf16_f32 v11, v11, v0
	ds_write_b16 v46, v11 offset:2816
	v_mul_f32_e32 v11, v13, v40
	v_cvt_pk_bf16_f32 v11, v11, v0
	ds_write_b16 v46, v11 offset:3840
	v_mul_f32_e32 v11, v62, v110
	v_cvt_pk_bf16_f32 v11, v11, v0
; #define LAS __attribute__((address_space(3)))
; __device__ __forceinline__ bf16_t f2bf(float f) { return (bf16_t)(cvt_pk_bf16(f, 0.f) & 0xffffu); }
; #define LBAR() do { asm volatile("s_waitcnt lgkmcnt(0)" ::: "memory"); __builtin_amdgcn_s_barrier(); asm volatile("" ::: "memory"); } while (0)
; __device__ __forceinline__ void retc_stream(const int wv, LAS unsigned char* lds, unsigned ldsb, const float* __restrict__ gn_g, const float* __restrict__ gn_b, const bf16_t* __restrict__ qkvr, const bf16_t* __restrict__ grb, const bf16_t* __restrict__ kv, ...
;     ...
;             for (int c = 0; c < 32; ++c) {
;                 const unsigned co = (unsigned)(((2 * c) ^ (2 * g)) * 16);
; #pragma unroll
;                 for (int e = 0; e < 4; ++e)
;                     *(LAS bf16_t*)(lds + wb + e * 1024 + co) = f2bf((acc[c][e] - mu4[e]) * rs4[e]);
;             }
;         }
;         {
;             int tq = t; asm volatile("" : "+v"(tq));
;             const int ch = tq & 63, r0 = tq >> 6;
;             const f32x4 g0 = *(const f32x4*)(gng + ch * 8), g1 = *(const f32x4*)(gng + ch * 8 + 4), b0 = *(const f32x4*)(gnb + ch * 8), b1 = *(const f32x4*)(gnb + ch * 8 + 4);
;             u32x4 gv[16];
; #pragma unroll
;             for (int k = 0; k < 16; ++k) gv[k] = *(const u32x4*)(grb + (size_t)(n * 128 + r0 + 8 * k) * 2048 + h * 512 + ch * 8);
;             LBAR();
	ds_write_b16 v41, v11 offset:768
	v_cvt_pk_bf16_f32 v10, v10, v0
	ds_write_b16 v41, v10 offset:1792
	v_mul_f32_e32 v10, v42, v1
	v_cvt_pk_bf16_f32 v10, v10, v0
	ds_write_b16 v41, v10 offset:2816
	v_mul_f32_e32 v10, v12, v40
	v_cvt_pk_bf16_f32 v10, v10, v0
	ds_write_b16 v41, v10 offset:3840
	v_mul_f32_e32 v10, v59, v110
	v_cvt_pk_bf16_f32 v10, v10, v0
	ds_write_b16 v44, v10 offset:896
	v_cvt_pk_bf16_f32 v7, v7, v0
	ds_write_b16 v44, v7 offset:1920
	v_mul_f32_e32 v7, v39, v1
	v_cvt_pk_bf16_f32 v7, v7, v0
	ds_write_b16 v44, v7 offset:2944
	v_mul_f32_e32 v7, v9, v40
	v_cvt_pk_bf16_f32 v7, v7, v0
	ds_write_b16 v44, v7 offset:3968
	v_mul_f32_e32 v7, v58, v110
	v_cvt_pk_bf16_f32 v7, v7, v0
	ds_write_b16 v45, v7 offset:896
	v_cvt_pk_bf16_f32 v6, v6, v0
	ds_write_b16 v45, v6 offset:1920
	v_mul_f32_e32 v6, v38, v1
	v_cvt_pk_bf16_f32 v6, v6, v0
	ds_write_b16 v45, v6 offset:2944
	v_mul_f32_e32 v6, v8, v40
	v_cvt_pk_bf16_f32 v6, v6, v0
	ds_write_b16 v45, v6 offset:3968
	v_mul_f32_e32 v6, v35, v110
	v_cvt_pk_bf16_f32 v6, v6, v0
	ds_write_b16 v46, v6 offset:896
	v_cvt_pk_bf16_f32 v3, v3, v0
	ds_write_b16 v46, v3 offset:1920
	v_mul_f32_e32 v3, v37, v1
	v_cvt_pk_bf16_f32 v3, v3, v0
	ds_write_b16 v46, v3 offset:2944
	v_mul_f32_e32 v3, v5, v40
	v_cvt_pk_bf16_f32 v3, v3, v0
	ds_write_b16 v46, v3 offset:3968
	v_mul_f32_e32 v3, v34, v110
	v_mul_f32_e32 v1, v36, v1
	v_cvt_pk_bf16_f32 v3, v3, v0
	ds_write_b16 v41, v3 offset:896
	v_cvt_pk_bf16_f32 v2, v2, v0
	ds_write_b16 v41, v2 offset:1920
	v_cvt_pk_bf16_f32 v1, v1, v0
	ds_write_b16 v41, v1 offset:2944
	v_mul_f32_e32 v1, v4, v40
	v_cvt_pk_bf16_f32 v1, v1, v0
	v_mov_b32_e32 v2, v191
	ds_write_b16 v41, v1 offset:3968
	v_mov_b32_e32 v79, v0
	v_and_b32_e32 v1, 63, v2
	v_lshlrev_b32_e32 v14, 5, v1
	v_ashrrev_i32_e32 v80, 6, v2
	global_load_dwordx4 v[2:5], v14, s[10:11] offset:16 nt
	global_load_dwordx4 v[10:13], v14, s[10:11] nt
	global_load_dwordx4 v[6:9], v14, s[0:1] offset:16 nt
	s_nop 0
	global_load_dwordx4 v[14:17], v14, s[0:1] nt
	s_lshl_b64 s[0:1], s[2:3], 1
	v_readlane_b32 s2, v254, 31
	v_add_u32_e32 v18, s29, v80
	s_add_u32 s2, s2, s0
	v_readlane_b32 s3, v254, 33
	s_addc_u32 s3, s3, s1
	v_lshlrev_b32_e32 v78, 4, v1
	v_ashrrev_i32_e32 v19, 31, v18
	v_lshl_add_u64 v[20:21], s[2:3], 0, v[78:79]
	v_lshlrev_b64 v[90:91], 12, v[18:19]
	v_lshl_add_u64 v[18:19], v[20:21], 0, v[90:91]
	global_load_dwordx4 v[82:85], v[18:19], off nt
	s_mov_b32 s2, 0x8000
	v_add_co_u32_e32 v20, vcc, s2, v18
	s_mov_b32 s2, 0x10000
	s_nop 0
	v_addc_co_u32_e32 v21, vcc, 0, v19, vcc
	global_load_dwordx4 v[74:77], v[20:21], off nt
	v_add_co_u32_e32 v20, vcc, s2, v18
	s_mov_b32 s2, 0x18000
	s_nop 0
	v_addc_co_u32_e32 v21, vcc, 0, v19, vcc
	global_load_dwordx4 v[70:73], v[20:21], off nt
	v_add_co_u32_e32 v20, vcc, s2, v18
	s_mov_b32 s2, 0x20000
	s_nop 0
	v_addc_co_u32_e32 v21, vcc, 0, v19, vcc
	global_load_dwordx4 v[66:69], v[20:21], off nt
	v_add_co_u32_e32 v20, vcc, s2, v18
	s_mov_b32 s2, 0x28000
	s_nop 0
	v_addc_co_u32_e32 v21, vcc, 0, v19, vcc
	global_load_dwordx4 v[62:65], v[20:21], off nt
	v_add_co_u32_e32 v20, vcc, s2, v18
	s_mov_b32 s2, 0x30000
	s_nop 0
	v_addc_co_u32_e32 v21, vcc, 0, v19, vcc
	global_load_dwordx4 v[58:61], v[20:21], off nt
	v_add_co_u32_e32 v20, vcc, s2, v18
	s_mov_b32 s2, 0x38000
	s_nop 0
	v_addc_co_u32_e32 v21, vcc, 0, v19, vcc
	global_load_dwordx4 v[54:57], v[20:21], off nt
	v_add_co_u32_e32 v20, vcc, s2, v18
	s_mov_b32 s2, 0x40000
	s_nop 0
	v_addc_co_u32_e32 v21, vcc, 0, v19, vcc
	global_load_dwordx4 v[50:53], v[20:21], off nt
	v_add_co_u32_e32 v20, vcc, s2, v18
	s_mov_b32 s2, 0x48000
	s_nop 0
	v_addc_co_u32_e32 v21, vcc, 0, v19, vcc
	global_load_dwordx4 v[46:49], v[20:21], off nt
	v_add_co_u32_e32 v20, vcc, s2, v18
	s_mov_b32 s2, 0x50000
	s_nop 0
	v_addc_co_u32_e32 v21, vcc, 0, v19, vcc
	global_load_dwordx4 v[42:45], v[20:21], off nt
	v_add_co_u32_e32 v20, vcc, s2, v18
	s_mov_b32 s2, 0x58000
	s_nop 0
	v_addc_co_u32_e32 v21, vcc, 0, v19, vcc
	global_load_dwordx4 v[38:41], v[20:21], off nt
	v_add_co_u32_e32 v20, vcc, s2, v18
	s_mov_b32 s2, 0x60000
	s_nop 0
	v_addc_co_u32_e32 v21, vcc, 0, v19, vcc
	global_load_dwordx4 v[34:37], v[20:21], off nt
	v_add_co_u32_e32 v20, vcc, s2, v18
	s_mov_b32 s2, 0x68000
	s_nop 0
	v_addc_co_u32_e32 v21, vcc, 0, v19, vcc
	global_load_dwordx4 v[30:33], v[20:21], off nt
	v_add_co_u32_e32 v20, vcc, s2, v18
	s_mov_b32 s2, 0x70000
	s_nop 0
	v_addc_co_u32_e32 v21, vcc, 0, v19, vcc
	global_load_dwordx4 v[26:29], v[20:21], off nt
	v_add_co_u32_e32 v20, vcc, s2, v18
	s_mov_b32 s2, 0x78000
	s_nop 0
	v_addc_co_u32_e32 v21, vcc, 0, v19, vcc
	v_lshrrev_b32_e32 v81, 1, v80
	v_add_co_u32_e32 v18, vcc, s2, v18
	v_bitop3_b32 v81, v81, v1, 6 bitop3:0x6c
	s_nop 0
	v_addc_co_u32_e32 v19, vcc, 0, v19, vcc
	v_lshlrev_b32_e32 v86, 10, v80
	v_lshlrev_b32_e32 v81, 4, v81
	global_load_dwordx4 v[22:25], v[20:21], off nt
	v_add3_u32 v86, 0, v86, v81
	global_load_dwordx4 v[18:21], v[18:19], off nt
	s_waitcnt lgkmcnt(0)
	s_barrier
; #define LAS __attribute__((address_space(3)))
; __device__ __forceinline__ unsigned cvt_pk_bf16(float lo, float hi) { unsigned r; asm volatile("v_cvt_pk_bf16_f32 %0, %1, %2" : "=v"(r) : "v"(lo), "v"(hi)); return r; }
; __device__ __forceinline__ float bflo(unsigned u) { return __uint_as_float(u << 16); }
; __device__ __forceinline__ float bfhi(unsigned u) { return __uint_as_float(u & 0xffff0000u); }
; __device__ __forceinline__ void retc_stream(const int wv, LAS unsigned char* lds, unsigned ldsb, const float* __restrict__ gn_g, const float* __restrict__ gn_b, const bf16_t* __restrict__ qkvr, const bf16_t* __restrict__ grb, const bf16_t* __restrict__ kv, ...
;     ...
; #pragma unroll
;             for (int k = 0; k < 16; ++k) {
;                 const int row = r0 + 8 * k;
;                 const u32x4 yv = *(const LAS u32x4*)(lds + row * 1024 + ((ch ^ (2 * ((row >> 2) & 3))) << 4));
;                 const u32x4 q = gv[k];
;                 u32x4 o;
;                 o.x = cvt_pk_bf16((bflo(yv.x) * g0[0] + b0[0]) * bflo(q.x), (bfhi(yv.x) * g0[1] + b0[1]) * bfhi(q.x));
;                 o.y = cvt_pk_bf16((bflo(yv.y) * g0[2] + b0[2]) * bflo(q.y), (bfhi(yv.y) * g0[3] + b0[3]) * bfhi(q.y));
;                 o.z = cvt_pk_bf16((bflo(yv.z) * g1[0] + b1[0]) * bflo(q.z), (bfhi(yv.z) * g1[1] + b1[1]) * bfhi(q.z));
;                 o.w = cvt_pk_bf16((bflo(yv.w) * g1[2] + b1[2]) * bflo(q.w), (bfhi(yv.w) * g1[3] + b1[3]) * bfhi(q.w));
;                 *(u32x4*)(orb + (size_t)(n * 128 + row) * 2048 + h * 512 + ch * 8) = o;
	ds_read_b128 v[86:89], v86
	s_waitcnt vmcnt(0)
	v_lshlrev_b32_e32 v93, 16, v82
	v_and_b32_e32 v82, 0xffff0000, v82
	v_readlane_b32 s2, v254, 35
	s_add_u32 s0, s2, s0
	s_waitcnt lgkmcnt(0)
	v_lshlrev_b32_e32 v92, 16, v86
	v_and_b32_e32 v86, 0xffff0000, v86
	v_fma_f32 v92, v10, v92, v14
	v_fma_f32 v86, v11, v86, v15
	v_mul_f32_e32 v92, v92, v93
	v_mul_f32_e32 v82, v86, v82
	v_lshlrev_b32_e32 v86, 16, v87
	v_and_b32_e32 v87, 0xffff0000, v87
	v_cvt_pk_bf16_f32 v82, v92, v82
	v_fma_f32 v86, v12, v86, v16
	v_lshlrev_b32_e32 v92, 16, v83
	v_fma_f32 v87, v13, v87, v17
	v_and_b32_e32 v83, 0xffff0000, v83
	v_mul_f32_e32 v86, v86, v92
	v_mul_f32_e32 v83, v87, v83
	v_cvt_pk_bf16_f32 v83, v86, v83
	v_lshlrev_b32_e32 v86, 16, v88
	v_fma_f32 v86, v2, v86, v6
	v_lshlrev_b32_e32 v87, 16, v84
	v_mul_f32_e32 v86, v86, v87
	v_and_b32_e32 v87, 0xffff0000, v88
	v_fma_f32 v87, v3, v87, v7
	v_and_b32_e32 v84, 0xffff0000, v84
	v_mul_f32_e32 v84, v87, v84
	v_cvt_pk_bf16_f32 v84, v86, v84
	v_lshlrev_b32_e32 v86, 16, v89
	v_fma_f32 v86, v4, v86, v8
	v_lshlrev_b32_e32 v87, 16, v85
	v_readlane_b32 s2, v254, 37
	v_mul_f32_e32 v86, v86, v87
	v_and_b32_e32 v87, 0xffff0000, v89
	s_addc_u32 s1, s2, s1
	v_fma_f32 v87, v5, v87, v9
	v_and_b32_e32 v85, 0xffff0000, v85
	v_lshl_add_u64 v[78:79], s[0:1], 0, v[78:79]
	v_mul_f32_e32 v85, v87, v85
	v_cvt_pk_bf16_f32 v85, v86, v85
	v_lshl_add_u64 v[86:87], v[78:79], 0, v[90:91]
	global_store_dwordx4 v[86:87], v[82:85], off nt
	v_add_u32_e32 v86, 8, v80
	v_lshlrev_b32_e32 v88, 16, v74
	v_lshrrev_b32_e32 v83, 1, v86
	v_bitop3_b32 v83, v83, v1, 6 bitop3:0x6c
	v_lshlrev_b32_e32 v82, 10, v86
	v_lshlrev_b32_e32 v83, 4, v83
	v_add3_u32 v82, 0, v82, v83
	ds_read_b128 v[82:85], v82
	v_and_b32_e32 v74, 0xffff0000, v74
	s_mov_b64 s[0:1], -1
	s_cmpk_gt_i32 s28, 0xff
	s_waitcnt lgkmcnt(0)
	v_lshlrev_b32_e32 v87, 16, v82
	v_and_b32_e32 v82, 0xffff0000, v82
	v_fma_f32 v87, v10, v87, v14
	v_fma_f32 v82, v11, v82, v15
	v_mul_f32_e32 v87, v87, v88
	v_mul_f32_e32 v74, v82, v74
	v_lshlrev_b32_e32 v82, 16, v83
	v_and_b32_e32 v83, 0xffff0000, v83
	v_cvt_pk_bf16_f32 v74, v87, v74
	v_fma_f32 v82, v12, v82, v16
	v_lshlrev_b32_e32 v87, 16, v75
	v_fma_f32 v83, v13, v83, v17
	v_and_b32_e32 v75, 0xffff0000, v75
	v_mul_f32_e32 v82, v82, v87
	v_mul_f32_e32 v75, v83, v75
	v_cvt_pk_bf16_f32 v75, v82, v75
	v_lshlrev_b32_e32 v82, 16, v84
	v_fma_f32 v82, v2, v82, v6
	v_lshlrev_b32_e32 v83, 16, v76
	v_mul_f32_e32 v82, v82, v83
	v_and_b32_e32 v83, 0xffff0000, v84
	v_fma_f32 v83, v3, v83, v7
	v_and_b32_e32 v76, 0xffff0000, v76
	v_mul_f32_e32 v76, v83, v76
	v_cvt_pk_bf16_f32 v76, v82, v76
	v_lshlrev_b32_e32 v82, 16, v85
	v_fma_f32 v82, v4, v82, v8
	v_lshlrev_b32_e32 v83, 16, v77
	v_mul_f32_e32 v82, v82, v83
	v_and_b32_e32 v83, 0xffff0000, v85
	v_fma_f32 v83, v5, v83, v9
	v_and_b32_e32 v77, 0xffff0000, v77
	v_mul_f32_e32 v77, v83, v77
	v_cvt_pk_bf16_f32 v77, v82, v77
	v_add_u32_e32 v82, s29, v86
	v_ashrrev_i32_e32 v83, 31, v82
	v_lshlrev_b64 v[82:83], 12, v[82:83]
	v_lshl_add_u64 v[82:83], v[78:79], 0, v[82:83]
	global_store_dwordx4 v[82:83], v[74:77], off nt
	v_add_u32_e32 v82, 16, v80
	v_lshlrev_b32_e32 v84, 16, v70
	v_lshlrev_b32_e32 v74, 10, v82
	v_add3_u32 v74, 0, v74, v81
	ds_read_b128 v[74:77], v74
	v_and_b32_e32 v70, 0xffff0000, v70
	s_waitcnt lgkmcnt(0)
	v_lshlrev_b32_e32 v83, 16, v74
	v_and_b32_e32 v74, 0xffff0000, v74
	v_fma_f32 v83, v10, v83, v14
	v_fma_f32 v74, v11, v74, v15
	v_mul_f32_e32 v83, v83, v84
	v_mul_f32_e32 v70, v74, v70
	v_lshlrev_b32_e32 v74, 16, v75
	v_and_b32_e32 v75, 0xffff0000, v75
	v_cvt_pk_bf16_f32 v70, v83, v70
	v_fma_f32 v74, v12, v74, v16
	v_lshlrev_b32_e32 v83, 16, v71
	v_fma_f32 v75, v13, v75, v17
	v_and_b32_e32 v71, 0xffff0000, v71
	v_mul_f32_e32 v74, v74, v83
	v_mul_f32_e32 v71, v75, v71
	v_cvt_pk_bf16_f32 v71, v74, v71
	v_lshlrev_b32_e32 v74, 16, v76
	v_fma_f32 v74, v2, v74, v6
	v_lshlrev_b32_e32 v75, 16, v72
	v_mul_f32_e32 v74, v74, v75
	v_and_b32_e32 v75, 0xffff0000, v76
	v_fma_f32 v75, v3, v75, v7
	v_and_b32_e32 v72, 0xffff0000, v72
	v_mul_f32_e32 v72, v75, v72
	v_cvt_pk_bf16_f32 v72, v74, v72
	v_lshlrev_b32_e32 v74, 16, v77
	v_fma_f32 v74, v4, v74, v8
	v_lshlrev_b32_e32 v75, 16, v73
	v_mul_f32_e32 v74, v74, v75
	v_and_b32_e32 v75, 0xffff0000, v77
	v_fma_f32 v75, v5, v75, v9
	v_and_b32_e32 v73, 0xffff0000, v73
	v_mul_f32_e32 v73, v75, v73
	v_cvt_pk_bf16_f32 v73, v74, v73
	v_add_u32_e32 v74, s29, v82
	v_ashrrev_i32_e32 v75, 31, v74
	v_lshlrev_b64 v[74:75], 12, v[74:75]
	v_lshl_add_u64 v[74:75], v[78:79], 0, v[74:75]
	global_store_dwordx4 v[74:75], v[70:73], off nt
	v_add_u32_e32 v74, 24, v80
	v_lshlrev_b32_e32 v76, 16, v66
	v_lshrrev_b32_e32 v71, 1, v74
	v_bitop3_b32 v71, v71, v1, 6 bitop3:0x6c
	v_lshlrev_b32_e32 v70, 10, v74
	v_lshlrev_b32_e32 v71, 4, v71
	v_add3_u32 v70, 0, v70, v71
	ds_read_b128 v[70:73], v70
	v_and_b32_e32 v66, 0xffff0000, v66
	s_waitcnt lgkmcnt(0)
	v_lshlrev_b32_e32 v75, 16, v70
	v_and_b32_e32 v70, 0xffff0000, v70
	v_fma_f32 v75, v10, v75, v14
	v_fma_f32 v70, v11, v70, v15
	v_mul_f32_e32 v75, v75, v76
	v_mul_f32_e32 v66, v70, v66
	v_lshlrev_b32_e32 v70, 16, v71
	v_and_b32_e32 v71, 0xffff0000, v71
	v_cvt_pk_bf16_f32 v66, v75, v66
	v_fma_f32 v70, v12, v70, v16
	v_lshlrev_b32_e32 v75, 16, v67
	v_fma_f32 v71, v13, v71, v17
	v_and_b32_e32 v67, 0xffff0000, v67
	v_mul_f32_e32 v70, v70, v75
	v_mul_f32_e32 v67, v71, v67
	v_cvt_pk_bf16_f32 v67, v70, v67
	v_lshlrev_b32_e32 v70, 16, v72
	v_fma_f32 v70, v2, v70, v6
	v_lshlrev_b32_e32 v71, 16, v68
	v_mul_f32_e32 v70, v70, v71
	v_and_b32_e32 v71, 0xffff0000, v72
	v_fma_f32 v71, v3, v71, v7
	v_and_b32_e32 v68, 0xffff0000, v68
	v_mul_f32_e32 v68, v71, v68
	v_cvt_pk_bf16_f32 v68, v70, v68
	v_lshlrev_b32_e32 v70, 16, v73
	v_fma_f32 v70, v4, v70, v8
	v_lshlrev_b32_e32 v71, 16, v69
	v_mul_f32_e32 v70, v70, v71
	v_and_b32_e32 v71, 0xffff0000, v73
	v_fma_f32 v71, v5, v71, v9
	v_and_b32_e32 v69, 0xffff0000, v69
	v_mul_f32_e32 v69, v71, v69
	v_cvt_pk_bf16_f32 v69, v70, v69
	v_add_u32_e32 v70, s29, v74
	v_ashrrev_i32_e32 v71, 31, v70
	v_lshlrev_b64 v[70:71], 12, v[70:71]
	v_lshl_add_u64 v[70:71], v[78:79], 0, v[70:71]
	global_store_dwordx4 v[70:71], v[66:69], off nt
	v_add_u32_e32 v70, 32, v80
	v_lshlrev_b32_e32 v72, 16, v62
	v_lshlrev_b32_e32 v66, 10, v70
	v_add3_u32 v66, 0, v66, v81
	ds_read_b128 v[66:69], v66
	v_and_b32_e32 v62, 0xffff0000, v62
	s_waitcnt lgkmcnt(0)
; #define LAS __attribute__((address_space(3)))
; __device__ __forceinline__ unsigned cvt_pk_bf16(float lo, float hi) { unsigned r; asm volatile("v_cvt_pk_bf16_f32 %0, %1, %2" : "=v"(r) : "v"(lo), "v"(hi)); return r; }
; __device__ __forceinline__ float bflo(unsigned u) { return __uint_as_float(u << 16); }
; __device__ __forceinline__ float bfhi(unsigned u) { return __uint_as_float(u & 0xffff0000u); }
; __device__ __forceinline__ void retc_stream(const int wv, LAS unsigned char* lds, unsigned ldsb, const float* __restrict__ gn_g, const float* __restrict__ gn_b, const bf16_t* __restrict__ qkvr, const bf16_t* __restrict__ grb, const bf16_t* __restrict__ kv, ...
;     ...
; #pragma unroll
;             for (int k = 0; k < 16; ++k) {
;                 const int row = r0 + 8 * k;
;                 const u32x4 yv = *(const LAS u32x4*)(lds + row * 1024 + ((ch ^ (2 * ((row >> 2) & 3))) << 4));
;                 const u32x4 q = gv[k];
;                 u32x4 o;
;                 o.x = cvt_pk_bf16((bflo(yv.x) * g0[0] + b0[0]) * bflo(q.x), (bfhi(yv.x) * g0[1] + b0[1]) * bfhi(q.x));
;                 o.y = cvt_pk_bf16((bflo(yv.y) * g0[2] + b0[2]) * bflo(q.y), (bfhi(yv.y) * g0[3] + b0[3]) * bfhi(q.y));
;                 o.z = cvt_pk_bf16((bflo(yv.z) * g1[0] + b1[0]) * bflo(q.z), (bfhi(yv.z) * g1[1] + b1[1]) * bfhi(q.z));
;                 o.w = cvt_pk_bf16((bflo(yv.w) * g1[2] + b1[2]) * bflo(q.w), (bfhi(yv.w) * g1[3] + b1[3]) * bfhi(q.w));
;                 *(u32x4*)(orb + (size_t)(n * 128 + row) * 2048 + h * 512 + ch * 8) = o;
	v_lshlrev_b32_e32 v71, 16, v66
	v_and_b32_e32 v66, 0xffff0000, v66
	v_fma_f32 v71, v10, v71, v14
	v_fma_f32 v66, v11, v66, v15
	v_mul_f32_e32 v71, v71, v72
	v_mul_f32_e32 v62, v66, v62
	v_lshlrev_b32_e32 v66, 16, v67
	v_and_b32_e32 v67, 0xffff0000, v67
	v_cvt_pk_bf16_f32 v62, v71, v62
	v_fma_f32 v66, v12, v66, v16
	v_lshlrev_b32_e32 v71, 16, v63
	v_fma_f32 v67, v13, v67, v17
	v_and_b32_e32 v63, 0xffff0000, v63
	v_mul_f32_e32 v66, v66, v71
	v_mul_f32_e32 v63, v67, v63
	v_cvt_pk_bf16_f32 v63, v66, v63
	v_lshlrev_b32_e32 v66, 16, v68
	v_fma_f32 v66, v2, v66, v6
	v_lshlrev_b32_e32 v67, 16, v64
	v_mul_f32_e32 v66, v66, v67
	v_and_b32_e32 v67, 0xffff0000, v68
	v_fma_f32 v67, v3, v67, v7
	v_and_b32_e32 v64, 0xffff0000, v64
	v_mul_f32_e32 v64, v67, v64
	v_cvt_pk_bf16_f32 v64, v66, v64
	v_lshlrev_b32_e32 v66, 16, v69
	v_fma_f32 v66, v4, v66, v8
	v_lshlrev_b32_e32 v67, 16, v65
	v_mul_f32_e32 v66, v66, v67
	v_and_b32_e32 v67, 0xffff0000, v69
	v_fma_f32 v67, v5, v67, v9
	v_and_b32_e32 v65, 0xffff0000, v65
	v_mul_f32_e32 v65, v67, v65
	v_cvt_pk_bf16_f32 v65, v66, v65
	v_add_u32_e32 v66, s29, v70
	v_ashrrev_i32_e32 v67, 31, v66
	v_lshlrev_b64 v[66:67], 12, v[66:67]
	v_lshl_add_u64 v[66:67], v[78:79], 0, v[66:67]
	global_store_dwordx4 v[66:67], v[62:65], off nt
	v_add_u32_e32 v66, 40, v80
	v_lshlrev_b32_e32 v68, 16, v58
	v_lshrrev_b32_e32 v63, 1, v66
	v_bitop3_b32 v63, v63, v1, 6 bitop3:0x6c
	v_lshlrev_b32_e32 v62, 10, v66
	v_lshlrev_b32_e32 v63, 4, v63
	v_add3_u32 v62, 0, v62, v63
	ds_read_b128 v[62:65], v62
	v_and_b32_e32 v58, 0xffff0000, v58
	s_waitcnt lgkmcnt(0)
	v_lshlrev_b32_e32 v67, 16, v62
	v_and_b32_e32 v62, 0xffff0000, v62
	v_fma_f32 v67, v10, v67, v14
	v_fma_f32 v62, v11, v62, v15
	v_mul_f32_e32 v67, v67, v68
	v_mul_f32_e32 v58, v62, v58
	v_lshlrev_b32_e32 v62, 16, v63
	v_and_b32_e32 v63, 0xffff0000, v63
	v_cvt_pk_bf16_f32 v58, v67, v58
	v_fma_f32 v62, v12, v62, v16
	v_lshlrev_b32_e32 v67, 16, v59
	v_fma_f32 v63, v13, v63, v17
	v_and_b32_e32 v59, 0xffff0000, v59
	v_mul_f32_e32 v62, v62, v67
	v_mul_f32_e32 v59, v63, v59
	v_cvt_pk_bf16_f32 v59, v62, v59
	v_lshlrev_b32_e32 v62, 16, v64
	v_fma_f32 v62, v2, v62, v6
	v_lshlrev_b32_e32 v63, 16, v60
	v_mul_f32_e32 v62, v62, v63
	v_and_b32_e32 v63, 0xffff0000, v64
	v_fma_f32 v63, v3, v63, v7
	v_and_b32_e32 v60, 0xffff0000, v60
	v_mul_f32_e32 v60, v63, v60
	v_cvt_pk_bf16_f32 v60, v62, v60
	v_lshlrev_b32_e32 v62, 16, v65
	v_fma_f32 v62, v4, v62, v8
	v_lshlrev_b32_e32 v63, 16, v61
	v_mul_f32_e32 v62, v62, v63
	v_and_b32_e32 v63, 0xffff0000, v65
	v_fma_f32 v63, v5, v63, v9
	v_and_b32_e32 v61, 0xffff0000, v61
	v_mul_f32_e32 v61, v63, v61
	v_cvt_pk_bf16_f32 v61, v62, v61
	v_add_u32_e32 v62, s29, v66
	v_ashrrev_i32_e32 v63, 31, v62
	v_lshlrev_b64 v[62:63], 12, v[62:63]
	v_lshl_add_u64 v[62:63], v[78:79], 0, v[62:63]
	global_store_dwordx4 v[62:63], v[58:61], off nt
	v_add_u32_e32 v62, 48, v80
	v_lshlrev_b32_e32 v64, 16, v54
	v_lshlrev_b32_e32 v58, 10, v62
	v_add3_u32 v58, 0, v58, v81
	ds_read_b128 v[58:61], v58
	v_and_b32_e32 v54, 0xffff0000, v54
	s_waitcnt lgkmcnt(0)
	v_lshlrev_b32_e32 v63, 16, v58
	v_and_b32_e32 v58, 0xffff0000, v58
	v_fma_f32 v63, v10, v63, v14
	v_fma_f32 v58, v11, v58, v15
	v_mul_f32_e32 v63, v63, v64
	v_mul_f32_e32 v54, v58, v54
	v_lshlrev_b32_e32 v58, 16, v59
	v_and_b32_e32 v59, 0xffff0000, v59
	v_cvt_pk_bf16_f32 v54, v63, v54
	v_fma_f32 v58, v12, v58, v16
	v_lshlrev_b32_e32 v63, 16, v55
	v_fma_f32 v59, v13, v59, v17
	v_and_b32_e32 v55, 0xffff0000, v55
	v_mul_f32_e32 v58, v58, v63
	v_mul_f32_e32 v55, v59, v55
	v_cvt_pk_bf16_f32 v55, v58, v55
	v_lshlrev_b32_e32 v58, 16, v60
	v_fma_f32 v58, v2, v58, v6
	v_lshlrev_b32_e32 v59, 16, v56
	v_mul_f32_e32 v58, v58, v59
	v_and_b32_e32 v59, 0xffff0000, v60
	v_fma_f32 v59, v3, v59, v7
	v_and_b32_e32 v56, 0xffff0000, v56
	v_mul_f32_e32 v56, v59, v56
	v_cvt_pk_bf16_f32 v56, v58, v56
	v_lshlrev_b32_e32 v58, 16, v61
	v_fma_f32 v58, v4, v58, v8
	v_lshlrev_b32_e32 v59, 16, v57
	v_mul_f32_e32 v58, v58, v59
	v_and_b32_e32 v59, 0xffff0000, v61
	v_fma_f32 v59, v5, v59, v9
	v_and_b32_e32 v57, 0xffff0000, v57
	v_mul_f32_e32 v57, v59, v57
	v_cvt_pk_bf16_f32 v57, v58, v57
	v_add_u32_e32 v58, s29, v62
	v_ashrrev_i32_e32 v59, 31, v58
	v_lshlrev_b64 v[58:59], 12, v[58:59]
	v_lshl_add_u64 v[58:59], v[78:79], 0, v[58:59]
	global_store_dwordx4 v[58:59], v[54:57], off nt
	v_add_u32_e32 v58, 56, v80
	v_lshlrev_b32_e32 v60, 16, v50
	v_lshrrev_b32_e32 v55, 1, v58
	v_bitop3_b32 v55, v55, v1, 6 bitop3:0x6c
	v_lshlrev_b32_e32 v54, 10, v58
	v_lshlrev_b32_e32 v55, 4, v55
	v_add3_u32 v54, 0, v54, v55
	ds_read_b128 v[54:57], v54
	v_and_b32_e32 v50, 0xffff0000, v50
	s_waitcnt lgkmcnt(0)
	v_lshlrev_b32_e32 v59, 16, v54
	v_and_b32_e32 v54, 0xffff0000, v54
	v_fma_f32 v59, v10, v59, v14
	v_fma_f32 v54, v11, v54, v15
	v_mul_f32_e32 v59, v59, v60
	v_mul_f32_e32 v50, v54, v50
	v_lshlrev_b32_e32 v54, 16, v55
	v_and_b32_e32 v55, 0xffff0000, v55
	v_cvt_pk_bf16_f32 v50, v59, v50
	v_fma_f32 v54, v12, v54, v16
	v_lshlrev_b32_e32 v59, 16, v51
	v_fma_f32 v55, v13, v55, v17
	v_and_b32_e32 v51, 0xffff0000, v51
	v_mul_f32_e32 v54, v54, v59
	v_mul_f32_e32 v51, v55, v51
	v_cvt_pk_bf16_f32 v51, v54, v51
	v_lshlrev_b32_e32 v54, 16, v56
	v_fma_f32 v54, v2, v54, v6
	v_lshlrev_b32_e32 v55, 16, v52
	v_mul_f32_e32 v54, v54, v55
	v_and_b32_e32 v55, 0xffff0000, v56
	v_fma_f32 v55, v3, v55, v7
	v_and_b32_e32 v52, 0xffff0000, v52
	v_mul_f32_e32 v52, v55, v52
	v_cvt_pk_bf16_f32 v52, v54, v52
	v_lshlrev_b32_e32 v54, 16, v57
	v_fma_f32 v54, v4, v54, v8
	v_lshlrev_b32_e32 v55, 16, v53
	v_mul_f32_e32 v54, v54, v55
	v_and_b32_e32 v55, 0xffff0000, v57
	v_fma_f32 v55, v5, v55, v9
	v_and_b32_e32 v53, 0xffff0000, v53
	v_mul_f32_e32 v53, v55, v53
	v_cvt_pk_bf16_f32 v53, v54, v53
	v_add_u32_e32 v54, s29, v58
	v_ashrrev_i32_e32 v55, 31, v54
	v_lshlrev_b64 v[54:55], 12, v[54:55]
	v_lshl_add_u64 v[54:55], v[78:79], 0, v[54:55]
	global_store_dwordx4 v[54:55], v[50:53], off nt
	v_add_u32_e32 v54, 64, v80
	v_lshlrev_b32_e32 v56, 16, v46
	v_lshlrev_b32_e32 v50, 10, v54
	v_add3_u32 v50, 0, v50, v81
	ds_read_b128 v[50:53], v50
	v_and_b32_e32 v46, 0xffff0000, v46
	s_waitcnt lgkmcnt(0)
; #define LAS __attribute__((address_space(3)))
; __device__ __forceinline__ unsigned cvt_pk_bf16(float lo, float hi) { unsigned r; asm volatile("v_cvt_pk_bf16_f32 %0, %1, %2" : "=v"(r) : "v"(lo), "v"(hi)); return r; }
; __device__ __forceinline__ float bflo(unsigned u) { return __uint_as_float(u << 16); }
; __device__ __forceinline__ float bfhi(unsigned u) { return __uint_as_float(u & 0xffff0000u); }
; __device__ __forceinline__ void retc_stream(const int wv, LAS unsigned char* lds, unsigned ldsb, const float* __restrict__ gn_g, const float* __restrict__ gn_b, const bf16_t* __restrict__ qkvr, const bf16_t* __restrict__ grb, const bf16_t* __restrict__ kv, ...
;     ...
; #pragma unroll
;             for (int k = 0; k < 16; ++k) {
;                 const int row = r0 + 8 * k;
;                 const u32x4 yv = *(const LAS u32x4*)(lds + row * 1024 + ((ch ^ (2 * ((row >> 2) & 3))) << 4));
;                 const u32x4 q = gv[k];
;                 u32x4 o;
;                 o.x = cvt_pk_bf16((bflo(yv.x) * g0[0] + b0[0]) * bflo(q.x), (bfhi(yv.x) * g0[1] + b0[1]) * bfhi(q.x));
;                 o.y = cvt_pk_bf16((bflo(yv.y) * g0[2] + b0[2]) * bflo(q.y), (bfhi(yv.y) * g0[3] + b0[3]) * bfhi(q.y));
;                 o.z = cvt_pk_bf16((bflo(yv.z) * g1[0] + b1[0]) * bflo(q.z), (bfhi(yv.z) * g1[1] + b1[1]) * bfhi(q.z));
;                 o.w = cvt_pk_bf16((bflo(yv.w) * g1[2] + b1[2]) * bflo(q.w), (bfhi(yv.w) * g1[3] + b1[3]) * bfhi(q.w));
;                 *(u32x4*)(orb + (size_t)(n * 128 + row) * 2048 + h * 512 + ch * 8) = o;
	v_lshlrev_b32_e32 v55, 16, v50
	v_and_b32_e32 v50, 0xffff0000, v50
	v_fma_f32 v55, v10, v55, v14
	v_fma_f32 v50, v11, v50, v15
	v_mul_f32_e32 v55, v55, v56
	v_mul_f32_e32 v46, v50, v46
	v_lshlrev_b32_e32 v50, 16, v51
	v_and_b32_e32 v51, 0xffff0000, v51
	v_cvt_pk_bf16_f32 v46, v55, v46
	v_fma_f32 v50, v12, v50, v16
	v_lshlrev_b32_e32 v55, 16, v47
	v_fma_f32 v51, v13, v51, v17
	v_and_b32_e32 v47, 0xffff0000, v47
	v_mul_f32_e32 v50, v50, v55
	v_mul_f32_e32 v47, v51, v47
	v_cvt_pk_bf16_f32 v47, v50, v47
	v_lshlrev_b32_e32 v50, 16, v52
	v_fma_f32 v50, v2, v50, v6
	v_lshlrev_b32_e32 v51, 16, v48
	v_mul_f32_e32 v50, v50, v51
	v_and_b32_e32 v51, 0xffff0000, v52
	v_fma_f32 v51, v3, v51, v7
	v_and_b32_e32 v48, 0xffff0000, v48
	v_mul_f32_e32 v48, v51, v48
	v_cvt_pk_bf16_f32 v48, v50, v48
	v_lshlrev_b32_e32 v50, 16, v53
	v_fma_f32 v50, v4, v50, v8
	v_lshlrev_b32_e32 v51, 16, v49
	v_mul_f32_e32 v50, v50, v51
	v_and_b32_e32 v51, 0xffff0000, v53
	v_fma_f32 v51, v5, v51, v9
	v_and_b32_e32 v49, 0xffff0000, v49
	v_mul_f32_e32 v49, v51, v49
	v_cvt_pk_bf16_f32 v49, v50, v49
	v_add_u32_e32 v50, s29, v54
	v_ashrrev_i32_e32 v51, 31, v50
	v_lshlrev_b64 v[50:51], 12, v[50:51]
	v_lshl_add_u64 v[50:51], v[78:79], 0, v[50:51]
	global_store_dwordx4 v[50:51], v[46:49], off nt
	v_add_u32_e32 v50, 0x48, v80
	v_lshlrev_b32_e32 v52, 16, v42
	v_lshrrev_b32_e32 v47, 1, v50
	v_bitop3_b32 v47, v47, v1, 6 bitop3:0x6c
	v_lshlrev_b32_e32 v46, 10, v50
	v_lshlrev_b32_e32 v47, 4, v47
	v_add3_u32 v46, 0, v46, v47
	ds_read_b128 v[46:49], v46
	v_and_b32_e32 v42, 0xffff0000, v42
	s_waitcnt lgkmcnt(0)
	v_lshlrev_b32_e32 v51, 16, v46
	v_and_b32_e32 v46, 0xffff0000, v46
	v_fma_f32 v51, v10, v51, v14
	v_fma_f32 v46, v11, v46, v15
	v_mul_f32_e32 v51, v51, v52
	v_mul_f32_e32 v42, v46, v42
	v_lshlrev_b32_e32 v46, 16, v47
	v_and_b32_e32 v47, 0xffff0000, v47
	v_cvt_pk_bf16_f32 v42, v51, v42
	v_fma_f32 v46, v12, v46, v16
	v_lshlrev_b32_e32 v51, 16, v43
	v_fma_f32 v47, v13, v47, v17
	v_and_b32_e32 v43, 0xffff0000, v43
	v_mul_f32_e32 v46, v46, v51
	v_mul_f32_e32 v43, v47, v43
	v_cvt_pk_bf16_f32 v43, v46, v43
	v_lshlrev_b32_e32 v46, 16, v48
	v_fma_f32 v46, v2, v46, v6
	v_lshlrev_b32_e32 v47, 16, v44
	v_mul_f32_e32 v46, v46, v47
	v_and_b32_e32 v47, 0xffff0000, v48
	v_fma_f32 v47, v3, v47, v7
	v_and_b32_e32 v44, 0xffff0000, v44
	v_mul_f32_e32 v44, v47, v44
	v_cvt_pk_bf16_f32 v44, v46, v44
	v_lshlrev_b32_e32 v46, 16, v49
	v_fma_f32 v46, v4, v46, v8
	v_lshlrev_b32_e32 v47, 16, v45
	v_mul_f32_e32 v46, v46, v47
	v_and_b32_e32 v47, 0xffff0000, v49
	v_fma_f32 v47, v5, v47, v9
	v_and_b32_e32 v45, 0xffff0000, v45
	v_mul_f32_e32 v45, v47, v45
	v_cvt_pk_bf16_f32 v45, v46, v45
	v_add_u32_e32 v46, s29, v50
	v_ashrrev_i32_e32 v47, 31, v46
	v_lshlrev_b64 v[46:47], 12, v[46:47]
	v_lshl_add_u64 v[46:47], v[78:79], 0, v[46:47]
	global_store_dwordx4 v[46:47], v[42:45], off nt
	v_add_u32_e32 v46, 0x50, v80
	v_lshlrev_b32_e32 v48, 16, v38
	v_lshlrev_b32_e32 v42, 10, v46
	v_add3_u32 v42, 0, v42, v81
	ds_read_b128 v[42:45], v42
	v_and_b32_e32 v38, 0xffff0000, v38
	s_waitcnt lgkmcnt(0)
	v_lshlrev_b32_e32 v47, 16, v42
	v_and_b32_e32 v42, 0xffff0000, v42
	v_fma_f32 v47, v10, v47, v14
	v_fma_f32 v42, v11, v42, v15
	v_mul_f32_e32 v47, v47, v48
	v_mul_f32_e32 v38, v42, v38
	v_lshlrev_b32_e32 v42, 16, v43
	v_and_b32_e32 v43, 0xffff0000, v43
	v_cvt_pk_bf16_f32 v38, v47, v38
	v_fma_f32 v42, v12, v42, v16
	v_lshlrev_b32_e32 v47, 16, v39
	v_fma_f32 v43, v13, v43, v17
	v_and_b32_e32 v39, 0xffff0000, v39
	v_mul_f32_e32 v42, v42, v47
	v_mul_f32_e32 v39, v43, v39
	v_cvt_pk_bf16_f32 v39, v42, v39
	v_lshlrev_b32_e32 v42, 16, v44
	v_fma_f32 v42, v2, v42, v6
	v_lshlrev_b32_e32 v43, 16, v40
	v_mul_f32_e32 v42, v42, v43
	v_and_b32_e32 v43, 0xffff0000, v44
	v_fma_f32 v43, v3, v43, v7
	v_and_b32_e32 v40, 0xffff0000, v40
	v_mul_f32_e32 v40, v43, v40
	v_cvt_pk_bf16_f32 v40, v42, v40
	v_lshlrev_b32_e32 v42, 16, v45
	v_fma_f32 v42, v4, v42, v8
	v_lshlrev_b32_e32 v43, 16, v41
	v_mul_f32_e32 v42, v42, v43
	v_and_b32_e32 v43, 0xffff0000, v45
	v_fma_f32 v43, v5, v43, v9
	v_and_b32_e32 v41, 0xffff0000, v41
	v_mul_f32_e32 v41, v43, v41
	v_cvt_pk_bf16_f32 v41, v42, v41
	v_add_u32_e32 v42, s29, v46
	v_ashrrev_i32_e32 v43, 31, v42
	v_lshlrev_b64 v[42:43], 12, v[42:43]
	v_lshl_add_u64 v[42:43], v[78:79], 0, v[42:43]
	global_store_dwordx4 v[42:43], v[38:41], off nt
	v_add_u32_e32 v42, 0x58, v80
	v_lshlrev_b32_e32 v44, 16, v34
	v_lshrrev_b32_e32 v39, 1, v42
	v_bitop3_b32 v39, v39, v1, 6 bitop3:0x6c
	v_lshlrev_b32_e32 v38, 10, v42
	v_lshlrev_b32_e32 v39, 4, v39
	v_add3_u32 v38, 0, v38, v39
	ds_read_b128 v[38:41], v38
	v_and_b32_e32 v34, 0xffff0000, v34
	s_waitcnt lgkmcnt(0)
	v_lshlrev_b32_e32 v43, 16, v38
	v_and_b32_e32 v38, 0xffff0000, v38
	v_fma_f32 v43, v10, v43, v14
	v_fma_f32 v38, v11, v38, v15
	v_mul_f32_e32 v43, v43, v44
	v_mul_f32_e32 v34, v38, v34
	v_lshlrev_b32_e32 v38, 16, v39
	v_and_b32_e32 v39, 0xffff0000, v39
	v_cvt_pk_bf16_f32 v34, v43, v34
	v_fma_f32 v38, v12, v38, v16
	v_lshlrev_b32_e32 v43, 16, v35
	v_fma_f32 v39, v13, v39, v17
	v_and_b32_e32 v35, 0xffff0000, v35
	v_mul_f32_e32 v38, v38, v43
	v_mul_f32_e32 v35, v39, v35
	v_cvt_pk_bf16_f32 v35, v38, v35
	v_lshlrev_b32_e32 v38, 16, v40
	v_fma_f32 v38, v2, v38, v6
	v_lshlrev_b32_e32 v39, 16, v36
	v_mul_f32_e32 v38, v38, v39
	v_and_b32_e32 v39, 0xffff0000, v40
	v_fma_f32 v39, v3, v39, v7
	v_and_b32_e32 v36, 0xffff0000, v36
	v_mul_f32_e32 v36, v39, v36
	v_cvt_pk_bf16_f32 v36, v38, v36
	v_lshlrev_b32_e32 v38, 16, v41
	v_fma_f32 v38, v4, v38, v8
	v_lshlrev_b32_e32 v39, 16, v37
	v_mul_f32_e32 v38, v38, v39
	v_and_b32_e32 v39, 0xffff0000, v41
	v_fma_f32 v39, v5, v39, v9
	v_and_b32_e32 v37, 0xffff0000, v37
	v_mul_f32_e32 v37, v39, v37
	v_cvt_pk_bf16_f32 v37, v38, v37
	v_add_u32_e32 v38, s29, v42
	v_ashrrev_i32_e32 v39, 31, v38
	v_lshlrev_b64 v[38:39], 12, v[38:39]
	v_lshl_add_u64 v[38:39], v[78:79], 0, v[38:39]
	global_store_dwordx4 v[38:39], v[34:37], off nt
	v_add_u32_e32 v38, 0x60, v80
	v_lshlrev_b32_e32 v40, 16, v30
	v_lshlrev_b32_e32 v34, 10, v38
	v_add3_u32 v34, 0, v34, v81
	ds_read_b128 v[34:37], v34
	v_and_b32_e32 v30, 0xffff0000, v30
	s_waitcnt lgkmcnt(0)
; #define LAS __attribute__((address_space(3)))
; __device__ __forceinline__ unsigned cvt_pk_bf16(float lo, float hi) { unsigned r; asm volatile("v_cvt_pk_bf16_f32 %0, %1, %2" : "=v"(r) : "v"(lo), "v"(hi)); return r; }
; __device__ __forceinline__ float bflo(unsigned u) { return __uint_as_float(u << 16); }
; __device__ __forceinline__ float bfhi(unsigned u) { return __uint_as_float(u & 0xffff0000u); }
; __device__ __forceinline__ void retc_stream(const int wv, LAS unsigned char* lds, unsigned ldsb, const float* __restrict__ gn_g, const float* __restrict__ gn_b, const bf16_t* __restrict__ qkvr, const bf16_t* __restrict__ grb, const bf16_t* __restrict__ kv, ...
;     ...
; #pragma unroll
;             for (int k = 0; k < 16; ++k) {
;                 const int row = r0 + 8 * k;
;                 const u32x4 yv = *(const LAS u32x4*)(lds + row * 1024 + ((ch ^ (2 * ((row >> 2) & 3))) << 4));
;                 const u32x4 q = gv[k];
;                 u32x4 o;
;                 o.x = cvt_pk_bf16((bflo(yv.x) * g0[0] + b0[0]) * bflo(q.x), (bfhi(yv.x) * g0[1] + b0[1]) * bfhi(q.x));
;                 o.y = cvt_pk_bf16((bflo(yv.y) * g0[2] + b0[2]) * bflo(q.y), (bfhi(yv.y) * g0[3] + b0[3]) * bfhi(q.y));
;                 o.z = cvt_pk_bf16((bflo(yv.z) * g1[0] + b1[0]) * bflo(q.z), (bfhi(yv.z) * g1[1] + b1[1]) * bfhi(q.z));
;                 o.w = cvt_pk_bf16((bflo(yv.w) * g1[2] + b1[2]) * bflo(q.w), (bfhi(yv.w) * g1[3] + b1[3]) * bfhi(q.w));
;                 *(u32x4*)(orb + (size_t)(n * 128 + row) * 2048 + h * 512 + ch * 8) = o;
;             }
;         }
;         if (inext >= count) break;
	v_lshlrev_b32_e32 v39, 16, v34
	v_and_b32_e32 v34, 0xffff0000, v34
	v_fma_f32 v39, v10, v39, v14
	v_fma_f32 v34, v11, v34, v15
	v_mul_f32_e32 v39, v39, v40
	v_mul_f32_e32 v30, v34, v30
	v_lshlrev_b32_e32 v34, 16, v35
	v_and_b32_e32 v35, 0xffff0000, v35
	v_cvt_pk_bf16_f32 v30, v39, v30
	v_fma_f32 v34, v12, v34, v16
	v_lshlrev_b32_e32 v39, 16, v31
	v_fma_f32 v35, v13, v35, v17
	v_and_b32_e32 v31, 0xffff0000, v31
	v_mul_f32_e32 v34, v34, v39
	v_mul_f32_e32 v31, v35, v31
	v_cvt_pk_bf16_f32 v31, v34, v31
	v_lshlrev_b32_e32 v34, 16, v36
	v_fma_f32 v34, v2, v34, v6
	v_lshlrev_b32_e32 v35, 16, v32
	v_mul_f32_e32 v34, v34, v35
	v_and_b32_e32 v35, 0xffff0000, v36
	v_fma_f32 v35, v3, v35, v7
	v_and_b32_e32 v32, 0xffff0000, v32
	v_mul_f32_e32 v32, v35, v32
	v_cvt_pk_bf16_f32 v32, v34, v32
	v_lshlrev_b32_e32 v34, 16, v37
	v_fma_f32 v34, v4, v34, v8
	v_lshlrev_b32_e32 v35, 16, v33
	v_mul_f32_e32 v34, v34, v35
	v_and_b32_e32 v35, 0xffff0000, v37
	v_fma_f32 v35, v5, v35, v9
	v_and_b32_e32 v33, 0xffff0000, v33
	v_mul_f32_e32 v33, v35, v33
	v_cvt_pk_bf16_f32 v33, v34, v33
	v_add_u32_e32 v34, s29, v38
	v_ashrrev_i32_e32 v35, 31, v34
	v_lshlrev_b64 v[34:35], 12, v[34:35]
	v_lshl_add_u64 v[34:35], v[78:79], 0, v[34:35]
	global_store_dwordx4 v[34:35], v[30:33], off nt
	v_add_u32_e32 v34, 0x68, v80
	v_lshlrev_b32_e32 v36, 16, v26
	v_lshrrev_b32_e32 v31, 1, v34
	v_bitop3_b32 v31, v31, v1, 6 bitop3:0x6c
	v_lshlrev_b32_e32 v30, 10, v34
	v_lshlrev_b32_e32 v31, 4, v31
	v_add3_u32 v30, 0, v30, v31
	ds_read_b128 v[30:33], v30
	v_and_b32_e32 v26, 0xffff0000, v26
	s_waitcnt lgkmcnt(0)
	v_lshlrev_b32_e32 v35, 16, v30
	v_and_b32_e32 v30, 0xffff0000, v30
	v_fma_f32 v35, v10, v35, v14
	v_fma_f32 v30, v11, v30, v15
	v_mul_f32_e32 v35, v35, v36
	v_mul_f32_e32 v26, v30, v26
	v_lshlrev_b32_e32 v30, 16, v31
	v_and_b32_e32 v31, 0xffff0000, v31
	v_cvt_pk_bf16_f32 v26, v35, v26
	v_fma_f32 v30, v12, v30, v16
	v_lshlrev_b32_e32 v35, 16, v27
	v_fma_f32 v31, v13, v31, v17
	v_and_b32_e32 v27, 0xffff0000, v27
	v_mul_f32_e32 v30, v30, v35
	v_mul_f32_e32 v27, v31, v27
	v_cvt_pk_bf16_f32 v27, v30, v27
	v_lshlrev_b32_e32 v30, 16, v32
	v_fma_f32 v30, v2, v30, v6
	v_lshlrev_b32_e32 v31, 16, v28
	v_mul_f32_e32 v30, v30, v31
	v_and_b32_e32 v31, 0xffff0000, v32
	v_fma_f32 v31, v3, v31, v7
	v_and_b32_e32 v28, 0xffff0000, v28
	v_mul_f32_e32 v28, v31, v28
	v_cvt_pk_bf16_f32 v28, v30, v28
	v_lshlrev_b32_e32 v30, 16, v33
	v_fma_f32 v30, v4, v30, v8
	v_lshlrev_b32_e32 v31, 16, v29
	v_mul_f32_e32 v30, v30, v31
	v_and_b32_e32 v31, 0xffff0000, v33
	v_fma_f32 v31, v5, v31, v9
	v_and_b32_e32 v29, 0xffff0000, v29
	v_mul_f32_e32 v29, v31, v29
	v_cvt_pk_bf16_f32 v29, v30, v29
	v_add_u32_e32 v30, s29, v34
	v_ashrrev_i32_e32 v31, 31, v30
	v_lshlrev_b64 v[30:31], 12, v[30:31]
	v_lshl_add_u64 v[30:31], v[78:79], 0, v[30:31]
	global_store_dwordx4 v[30:31], v[26:29], off nt
	v_add_u32_e32 v30, 0x70, v80
	v_lshlrev_b32_e32 v32, 16, v22
	v_lshlrev_b32_e32 v26, 10, v30
	v_add3_u32 v26, 0, v26, v81
	ds_read_b128 v[26:29], v26
	v_and_b32_e32 v22, 0xffff0000, v22
	s_waitcnt lgkmcnt(0)
	v_lshlrev_b32_e32 v31, 16, v26
	v_and_b32_e32 v26, 0xffff0000, v26
	v_fma_f32 v31, v10, v31, v14
	v_fma_f32 v26, v11, v26, v15
	v_mul_f32_e32 v31, v31, v32
	v_mul_f32_e32 v22, v26, v22
	v_lshlrev_b32_e32 v26, 16, v27
	v_and_b32_e32 v27, 0xffff0000, v27
	v_cvt_pk_bf16_f32 v22, v31, v22
	v_fma_f32 v26, v12, v26, v16
	v_lshlrev_b32_e32 v31, 16, v23
	v_fma_f32 v27, v13, v27, v17
	v_and_b32_e32 v23, 0xffff0000, v23
	v_mul_f32_e32 v26, v26, v31
	v_mul_f32_e32 v23, v27, v23
	v_cvt_pk_bf16_f32 v23, v26, v23
	v_lshlrev_b32_e32 v26, 16, v28
	v_fma_f32 v26, v2, v26, v6
	v_lshlrev_b32_e32 v27, 16, v24
	v_mul_f32_e32 v26, v26, v27
	v_and_b32_e32 v27, 0xffff0000, v28
	v_fma_f32 v27, v3, v27, v7
	v_and_b32_e32 v24, 0xffff0000, v24
	v_mul_f32_e32 v24, v27, v24
	v_cvt_pk_bf16_f32 v24, v26, v24
	v_lshlrev_b32_e32 v26, 16, v29
	v_fma_f32 v26, v4, v26, v8
	v_lshlrev_b32_e32 v27, 16, v25
	v_mul_f32_e32 v26, v26, v27
	v_and_b32_e32 v27, 0xffff0000, v29
	v_fma_f32 v27, v5, v27, v9
	v_and_b32_e32 v25, 0xffff0000, v25
	v_mul_f32_e32 v25, v27, v25
	v_cvt_pk_bf16_f32 v25, v26, v25
	v_add_u32_e32 v26, s29, v30
	v_ashrrev_i32_e32 v27, 31, v26
	v_lshlrev_b64 v[26:27], 12, v[26:27]
	v_lshl_add_u64 v[26:27], v[78:79], 0, v[26:27]
	global_store_dwordx4 v[26:27], v[22:25], off nt
	v_add_u32_e32 v26, 0x78, v80
	s_nop 0
	v_lshrrev_b32_e32 v23, 1, v26
	v_bitop3_b32 v1, v23, v1, 6 bitop3:0x6c
	v_lshlrev_b32_e32 v22, 10, v26
	v_lshlrev_b32_e32 v1, 4, v1
	v_add3_u32 v1, 0, v22, v1
	ds_read_b128 v[22:25], v1
	s_waitcnt lgkmcnt(0)
	v_lshlrev_b32_e32 v1, 16, v22
	v_fma_f32 v1, v10, v1, v14
	v_lshlrev_b32_e32 v10, 16, v18
	v_mul_f32_e32 v1, v1, v10
	v_and_b32_e32 v10, 0xffff0000, v22
	v_fma_f32 v10, v11, v10, v15
	v_and_b32_e32 v11, 0xffff0000, v18
	v_mul_f32_e32 v10, v10, v11
	v_cvt_pk_bf16_f32 v10, v1, v10
	v_lshlrev_b32_e32 v1, 16, v23
	v_fma_f32 v1, v12, v1, v16
	v_lshlrev_b32_e32 v11, 16, v19
	v_mul_f32_e32 v1, v1, v11
	v_and_b32_e32 v11, 0xffff0000, v23
	v_fmac_f32_e32 v17, v13, v11
	v_and_b32_e32 v11, 0xffff0000, v19
	v_mul_f32_e32 v11, v17, v11
	v_cvt_pk_bf16_f32 v11, v1, v11
	v_lshlrev_b32_e32 v1, 16, v24
	v_fma_f32 v1, v2, v1, v6
	v_lshlrev_b32_e32 v2, 16, v20
	v_mul_f32_e32 v1, v1, v2
	v_and_b32_e32 v2, 0xffff0000, v24
	v_fma_f32 v2, v3, v2, v7
	v_and_b32_e32 v3, 0xffff0000, v20
	v_mul_f32_e32 v2, v2, v3
	v_cvt_pk_bf16_f32 v12, v1, v2
	v_lshlrev_b32_e32 v1, 16, v25
	v_fma_f32 v1, v4, v1, v8
	v_lshlrev_b32_e32 v2, 16, v21
	v_mul_f32_e32 v1, v1, v2
	v_and_b32_e32 v2, 0xffff0000, v25
	v_fmac_f32_e32 v9, v5, v2
	v_and_b32_e32 v2, 0xffff0000, v21
	v_mul_f32_e32 v2, v9, v2
	v_cvt_pk_bf16_f32 v13, v1, v2
	v_add_u32_e32 v2, s29, v26
	v_ashrrev_i32_e32 v3, 31, v2
	v_lshlrev_b64 v[2:3], 12, v[2:3]
	v_lshl_add_u64 v[2:3], v[78:79], 0, v[2:3]
	global_store_dwordx4 v[2:3], v[10:13], off nt
	s_cbranch_scc1 .LBB0_468
; #define LBAR() do { asm volatile("s_waitcnt lgkmcnt(0)" ::: "memory"); __builtin_amdgcn_s_barrier(); asm volatile("" ::: "memory"); } while (0)
; __device__ __forceinline__ void retc_stream(const int wv, LAS unsigned char* lds, unsigned ldsb, const float* __restrict__ gn_g, const float* __restrict__ gn_b, const bf16_t* __restrict__ qkvr, const bf16_t* __restrict__ grb, const bf16_t* __restrict__ kv, ...
;     ...
;         if (inext >= count) break;
;         LBAR();
;         RETC_ISSUE(inext, 0);
;         item = inext;
	s_and_b32 s1, s60, 0x1f80
	s_and_b32 s0, s61, 0xffffff00
	s_mulk_i32 s1, 0x4400
	s_add_u32 s2, s82, s1
	s_addc_u32 s3, s39, 0
	s_ashr_i32 s1, s0, 31
	s_lshl_b64 s[0:1], s[0:1], 1
	s_add_u32 s0, s2, s0
	s_addc_u32 s1, s3, s1
	v_lshl_add_u64 v[2:3], s[0:1], 0, v[180:181]
	s_mov_b64 s[0:1], 0x2400
	s_mov_b32 m0, s58
	s_waitcnt lgkmcnt(0)
	s_barrier
	v_lshl_add_u64 v[4:5], v[2:3], 0, s[0:1]
	s_mov_b64 s[0:1], 0x46400
	global_load_lds_dwordx4 v[4:5], off nt
	v_lshl_add_u64 v[4:5], v[2:3], 0, s[0:1]
	s_mov_b32 m0, s47
	s_mov_b64 s[0:1], 0x8a400
	global_load_lds_dwordx4 v[4:5], off nt
	v_lshl_add_u64 v[4:5], v[2:3], 0, s[0:1]
	s_mov_b32 m0, s24
	s_mov_b64 s[0:1], 0xce400
	global_load_lds_dwordx4 v[4:5], off nt
	v_lshl_add_u64 v[4:5], v[2:3], 0, s[0:1]
	s_mov_b32 m0, s25
	s_mov_b64 s[0:1], 0x112400
	global_load_lds_dwordx4 v[4:5], off nt
	v_lshl_add_u64 v[4:5], v[2:3], 0, s[0:1]
	s_mov_b32 m0, s48
	s_mov_b64 s[0:1], 0x156400
	global_load_lds_dwordx4 v[4:5], off nt
	v_lshl_add_u64 v[4:5], v[2:3], 0, s[0:1]
	s_mov_b32 m0, s49
	s_mov_b64 s[0:1], 0x19a400
	global_load_lds_dwordx4 v[4:5], off nt
	v_lshl_add_u64 v[4:5], v[2:3], 0, s[0:1]
	s_mov_b32 m0, s50
	s_mov_b64 s[0:1], 0x1de400
	global_load_lds_dwordx4 v[4:5], off nt
	v_lshl_add_u64 v[2:3], v[2:3], 0, s[0:1]
	s_mov_b32 m0, s51
	v_readlane_b32 s0, v253, 62
	global_load_lds_dwordx4 v[2:3], off nt
	v_readlane_b32 s1, v253, 63
	s_nop 1
	v_lshl_add_u64 v[182:183], v[182:183], 0, s[0:1]
	v_readlane_b32 s0, v253, 55
	s_add_i32 s61, s61, s0
	v_readlane_b32 s0, v253, 57
	s_add_i32 s60, s60, s0
	s_mov_b64 s[0:1], 0
	s_branch .LBB0_468
